# attention K/V rows shared by the workgroup through LDS (LDS-DMA ring of 3 window rows + 4 resident context rows, one barrier per 32-key step, fragments read from LDS one step ahead); static LDS 16384
# speedup vs baseline: 1.0880x; 1.0114x over previous
.LBB0_465:
	v_add_f32_e32 v1, v1, v4
	v_mul_f32_e32 v4, 0x4f800000, v1
	v_cmp_gt_f32_e32 vcc, s70, v1
	v_add_f32_e32 v2, v2, v3
	v_mul_f32_e32 v3, 0x4f800000, v2
	v_cndmask_b32_e32 v1, v1, v4, vcc
	v_sqrt_f32_e32 v4, v1
	s_mul_i32 s82, s82, 0x88000
	s_lshl_b32 s81, s7, 1
	s_mov_b32 s42, s26
	v_add_u32_e32 v9, -1, v4
	v_fma_f32 v10, -v9, v4, v1
	v_cmp_ge_f32_e64 s[0:1], 0, v10
	v_add_u32_e32 v10, 1, v4
	s_mov_b32 s43, s27
	v_cndmask_b32_e64 v9, v4, v9, s[0:1]
	v_fma_f32 v4, -v10, v4, v1
	v_cmp_lt_f32_e64 s[0:1], 0, v4
	s_or_b32 s20, s5, 1
	s_and_b32 s4, s4, 15
	v_cndmask_b32_e64 v4, v9, v10, s[0:1]
	v_mul_f32_e32 v9, 0x37800000, v4
	v_cndmask_b32_e32 v4, v4, v9, vcc
	v_cmp_gt_f32_e32 vcc, s70, v2
	v_cmp_class_f32_e64 s[0:1], v1, v237
	s_lshl_b32 s4, s4, 10
	v_cndmask_b32_e32 v2, v2, v3, vcc
	v_sqrt_f32_e32 v3, v2
	v_cndmask_b32_e64 v1, v4, v1, s[0:1]
	s_waitcnt lgkmcnt(8)
	v_fma_f32 v1, v227, v1, v228
	v_mov_b32_e32 v224, 0
	v_add_u32_e32 v4, -1, v3
	v_fma_f32 v9, -v4, v3, v2
	v_cmp_ge_f32_e64 s[0:1], 0, v9
	v_add_u32_e32 v9, 1, v3
	s_mov_b32 s92, 0
	v_cndmask_b32_e64 v4, v3, v4, s[0:1]
	v_fma_f32 v3, -v9, v3, v2
	v_cmp_lt_f32_e64 s[0:1], 0, v3
	s_add_i32 s83, s83, 20
	s_add_i32 s84, s75, 4
	v_cndmask_b32_e64 v3, v4, v9, s[0:1]
	v_mul_f32_e32 v4, 0x37800000, v3
	v_cndmask_b32_e32 v3, v3, v4, vcc
	v_add_f32_e32 v4, v5, v6
	v_mul_f32_e32 v5, 0x4f800000, v4
	v_cmp_gt_f32_e32 vcc, s70, v4
	v_cmp_class_f32_e64 s[0:1], v2, v237
	v_mov_b32_e32 v225, v224
	v_cndmask_b32_e32 v4, v4, v5, vcc
	v_sqrt_f32_e32 v5, v4
	v_cndmask_b32_e64 v2, v3, v2, s[0:1]
	v_fma_f32 v2, v227, v2, v228
	v_max3_f32 v1, v1, 0, v2
	v_add_u32_e32 v2, -1, v5
	v_fma_f32 v3, -v2, v5, v4
	v_cmp_ge_f32_e64 s[0:1], 0, v3
	v_add_u32_e32 v3, 1, v5
	v_mov_b32_e32 v222, v224
	v_cndmask_b32_e64 v2, v5, v2, s[0:1]
	v_fma_f32 v5, -v3, v5, v4
	v_cmp_lt_f32_e64 s[0:1], 0, v5
	v_mov_b32_e32 v223, v224
	s_nop 0
	v_cndmask_b32_e64 v2, v2, v3, s[0:1]
	v_mul_f32_e32 v3, 0x37800000, v2
	s_lshl_b32 s0, s8, 1
	v_cndmask_b32_e32 v2, v2, v3, vcc
	v_cmp_class_f32_e32 vcc, v4, v237
	v_add_f32_e32 v3, v7, v8
	s_add_i32 s0, s0, s82
	v_cndmask_b32_e32 v2, v2, v4, vcc
	v_mul_f32_e32 v4, 0x4f800000, v3
	v_cmp_gt_f32_e32 vcc, s70, v3
	s_add_i32 s7, s0, 0x44000
	s_add_i32 s1, s0, 0x4c800
	v_cndmask_b32_e32 v3, v3, v4, vcc
	s_add_i32 s9, s0, 0x8800
	v_sqrt_f32_e32 v52, v3
	v_fma_f32 v2, v227, v2, v228
	v_add_u32_e32 v53, -1, v52
	v_fma_f32 v54, -v53, v52, v3
	v_cmp_ge_f32_e64 s[0:1], 0, v54
	v_add_u32_e32 v54, 1, v52
	s_nop 0
	v_cndmask_b32_e64 v53, v52, v53, s[0:1]
	v_fma_f32 v52, -v54, v52, v3
	v_cmp_lt_f32_e64 s[0:1], 0, v52
	s_nop 1
	v_cndmask_b32_e64 v52, v53, v54, s[0:1]
	v_mul_f32_e32 v53, 0x37800000, v52
	v_cndmask_b32_e32 v52, v52, v53, vcc
	v_cmp_class_f32_e32 vcc, v3, v237
	s_nop 1
	v_cndmask_b32_e32 v3, v52, v3, vcc
	v_fma_f32 v3, v227, v3, v228
	v_max3_f32 v239, v1, v2, v3
	v_add_u32_e32 v1, s59, v232
	v_sub_u32_e32 v1, v229, v1
	v_add_u32_e32 v2, 15, v1
	v_cmp_gt_u32_e64 s[0:1], 16, v2
	v_add_u32_e32 v2, 14, v1
	v_cmp_gt_u32_e64 s[6:7], 16, v2
	v_add_u32_e32 v2, 13, v1
	v_cmp_gt_u32_e64 s[8:9], 16, v2
	v_add_u32_e32 v2, 12, v1
	v_cmp_gt_u32_e64 s[10:11], 16, v2
	v_add_u32_e32 v2, 11, v1
	v_cmp_gt_u32_e64 s[12:13], 16, v2
	v_add_u32_e32 v2, 10, v1
	v_cmp_gt_u32_e64 s[14:15], 16, v2
	v_add_u32_e32 v2, 9, v1
	v_add_u32_e32 v1, 8, v1
	v_cmp_gt_u32_e64 s[18:19], 16, v1
	v_sub_u32_e64 v1, s20, 4 clamp
	v_cmp_gt_u32_e64 s[16:17], 16, v2
	v_readfirstlane_b32 s20, v1
	s_min_u32 s85, s20, 56
	s_or_b32 s20, s5, 2
	v_sub_u32_e64 v1, s20, 4 clamp
	s_or_b32 s5, s5, 3
	v_readfirstlane_b32 s20, v1
	v_sub_u32_e64 v1, s5, 4 clamp
	s_min_u32 s87, s20, 56
	v_readfirstlane_b32 s5, v1
	s_min_u32 s89, s5, 56
	s_lshl_b32 s5, s75, 8
	s_lshl_b32 s20, s59, 2
	s_or_b32 s5, s5, s20
	v_lshrrev_b32_e32 v85, 4, v226
	v_and_b32_e32 v86, 15, v226
	v_lshlrev_b32_e32 v233, 9, v85
	v_lshl_add_u32 v233, v86, 4, v233
	v_lshlrev_b32_e32 v234, 4, v226
	v_bfe_u32 v87, v226, 2, 3
	v_lshrrev_b32_e32 v220, 5, v226
	v_lshl_add_u32 v87, v87, 3, v220
	v_and_b32_e32 v221, 3, v226
	v_lshlrev_b32_e32 v221, 4, v221
	v_lshl_add_u32 v235, v87, 10, v221
	v_bfe_u32 v87, v226, 2, 2
	v_lshl_add_u32 v87, v87, 3, v85
	v_mul_u32_u24_e32 v87, 0x2200, v87
	v_add_u32_e32 v250, v87, v221
	v_readfirstlane_b32 s21, v231
	s_nop 3
	s_sub_u32 s21, s21, 0x8000
	s_lshr_b32 s86, s21, 13
	s_lshl_b32 s84, s86, 10
	s_lshr_b32 s20, s86, 2
	s_lshl_b32 s20, s20, 12
	s_and_b32 s21, s86, 1
	s_lshl_b32 s21, s21, 11
	s_add_u32 s20, s20, s21
	s_bfe_u32 s21, s86, 0x10001
	s_lshl_b32 s21, s21, 6
	s_add_u32 s20, s20, s21
	s_add_u32 s61, s20, s81
	s_lshr_b32 s20, s86, 2
	s_mul_i32 s20, s20, 0x44000
	s_bfe_u32 s21, s86, 0x10001
	s_mul_i32 s21, s21, 0x8800
	s_add_u32 s20, s20, s21
	s_and_b32 s21, s86, 1
	s_lshl_b32 s21, s21, 6
	s_add_u32 s20, s20, s21
	s_add_u32 s62, s20, s82
	s_lshr_b32 s20, s77, 2
	s_add_u32 s20, s20, 1
	s_cmp_eq_u32 s76, 8
	s_cselect_b32 s21, 1, 0
	s_cmp_eq_u32 s77, 0
	s_cselect_b32 s22, 1, 0
	s_and_b32 s21, s21, s22
	s_sub_u32 s20, s20, s21
	s_and_b32 s21, s20, 1
	s_lshl_b32 s22, s20, 2
	s_sub_i32 s22, s22, 8
	s_max_i32 s22, s22, 0
	s_sub_i32 s22, s77, s22
	s_cmp_eq_u32 s21, 1
	s_cselect_b32 s60, s22, 0
	s_sub_i32 s93, s77, s60
	s_and_b32 s20, s20, 14
	s_cmp_eq_u32 s20, 0
	s_cselect_b32 s22, 11, 15
	s_cmp_eq_u32 s20, 14
	s_cselect_b32 s80, 12, s22
	s_lshl_b32 s97, s59, 3
	s_lshl_b32 s90, s59, 5
	s_add_u32 s90, s90, 0x2000
	s_add_u32 s20, s93, 0
	s_mov_b32 s88, 0x18000
	s_lshl_b32 s21, s20, 16
	s_add_u32 s21, s21, s61
	s_lshl_b32 s22, s20, 7
	s_add_u32 s22, s22, s62
	s_add_u32 m0, s88, s84
	s_add_u32 s86, s88, s84
	s_add_u32 s86, s86, 0x2000
	buffer_load_dwordx4 v235, s[24:27], s21 offen lds
	s_mov_b32 m0, s86
	s_nop 0
	buffer_load_dwordx4 v250, s[40:43], s22 offen lds
	s_add_u32 s20, s93, 1
	s_mov_b32 s88, 0x1c000
	s_lshl_b32 s21, s20, 16
	s_add_u32 s21, s21, s61
	s_lshl_b32 s22, s20, 7
	s_add_u32 s22, s22, s62
	s_add_u32 m0, s88, s84
	s_add_u32 s86, s88, s84
	s_add_u32 s86, s86, 0x2000
	buffer_load_dwordx4 v235, s[24:27], s21 offen lds
	s_mov_b32 m0, s86
	s_nop 0
	buffer_load_dwordx4 v250, s[40:43], s22 offen lds
	s_add_u32 s20, s93, 2
	s_mov_b32 s88, 0x20010
	s_lshl_b32 s21, s20, 16
	s_add_u32 s21, s21, s61
	s_lshl_b32 s22, s20, 7
	s_add_u32 s22, s22, s62
	s_add_u32 m0, s88, s84
	s_add_u32 s86, s88, s84
	s_add_u32 s86, s86, 0x2000
	buffer_load_dwordx4 v235, s[24:27], s21 offen lds
	s_mov_b32 m0, s86
	s_nop 0
	buffer_load_dwordx4 v250, s[40:43], s22 offen lds
	s_sub_i32 s4, s5, s4
	v_add_u32_e32 v240, s4, v236
	ds_read_b128 v[132:135], v231 offset:0
	ds_read_b128 v[136:139], v231 offset:1024
	ds_read_b128 v[140:143], v231 offset:2048
	ds_read_b128 v[144:147], v231 offset:3072
	ds_read_b128 v[148:151], v231 offset:4096
	ds_read_b128 v[152:155], v231 offset:5120
	ds_read_b128 v[156:159], v231 offset:6144
	ds_read_b128 v[160:163], v231 offset:7168
	ds_read2_b32 v[204:205], v240 offset0:192 offset1:193
	ds_read2_b32 v[206:207], v240 offset0:194 offset1:195
	ds_read2_b32 v[208:209], v240 offset0:196 offset1:197
	ds_read2_b32 v[210:211], v240 offset0:198 offset1:199
	ds_read2_b32 v[80:81], v240 offset0:128 offset1:129
	ds_read2_b32 v[82:83], v240 offset0:130 offset1:131
	ds_read2_b32 v[84:85], v240 offset0:132 offset1:133
	ds_read2_b32 v[86:87], v240 offset0:134 offset1:135
	ds_read2_b32 v[180:181], v240 offset0:64 offset1:65
	ds_read2_b32 v[182:183], v240 offset0:66 offset1:67
	ds_read2_b32 v[184:185], v240 offset0:68 offset1:69
	ds_read2_b32 v[186:187], v240 offset0:70 offset1:71
	ds_read2_b32 v[212:213], v240 offset0:0 offset1:1
	ds_read2_b32 v[214:215], v240 offset0:2 offset1:3
	ds_read2_b32 v[242:243], v240 offset0:4 offset1:5
	ds_read2_b32 v[244:245], v240 offset0:6 offset1:7
	v_xor_b32_e32 v76, 0x80000000, v239
	v_xor_b32_e32 v77, 0x80000000, v239
	v_xor_b32_e32 v78, 0x80000000, v239
	v_xor_b32_e32 v79, 0x80000000, v239
	v_mov_b32_e32 v96, 0
	v_mov_b32_e32 v97, 0
	v_mov_b32_e32 v98, 0
	v_mov_b32_e32 v99, 0
	v_mov_b32_e32 v88, 0
	v_mov_b32_e32 v89, 0
	v_mov_b32_e32 v90, 0
	v_mov_b32_e32 v91, 0
	v_mov_b32_e32 v72, 0
	v_mov_b32_e32 v73, 0
	v_mov_b32_e32 v74, 0
	v_mov_b32_e32 v75, 0
	v_mov_b32_e32 v68, 0
	v_mov_b32_e32 v69, 0
	v_mov_b32_e32 v70, 0
	v_mov_b32_e32 v71, 0
	v_mov_b32_e32 v222, 0
	v_mov_b32_e32 v64, 0
	v_mov_b32_e32 v65, 0
	v_mov_b32_e32 v66, 0
	v_mov_b32_e32 v67, 0
	v_mov_b32_e32 v60, 0
	v_mov_b32_e32 v61, 0
	v_mov_b32_e32 v62, 0
	v_mov_b32_e32 v63, 0
	v_mov_b32_e32 v56, 0
	v_mov_b32_e32 v57, 0
	v_mov_b32_e32 v58, 0
	v_mov_b32_e32 v59, 0
	v_mov_b32_e32 v52, 0
	v_mov_b32_e32 v53, 0
	v_mov_b32_e32 v54, 0
	v_mov_b32_e32 v55, 0
	v_mov_b32_e32 v223, 0
	v_mov_b32_e32 v128, 0
	v_mov_b32_e32 v129, 0
	v_mov_b32_e32 v130, 0
	v_mov_b32_e32 v131, 0
	v_mov_b32_e32 v124, 0
	v_mov_b32_e32 v125, 0
	v_mov_b32_e32 v126, 0
	v_mov_b32_e32 v127, 0
	v_mov_b32_e32 v120, 0
	v_mov_b32_e32 v121, 0
	v_mov_b32_e32 v122, 0
	v_mov_b32_e32 v123, 0
	v_mov_b32_e32 v116, 0
	v_mov_b32_e32 v117, 0
	v_mov_b32_e32 v118, 0
	v_mov_b32_e32 v119, 0
	v_mov_b32_e32 v224, 0
	v_mov_b32_e32 v112, 0
	v_mov_b32_e32 v113, 0
	v_mov_b32_e32 v114, 0
	v_mov_b32_e32 v115, 0
	v_mov_b32_e32 v108, 0
	v_mov_b32_e32 v109, 0
	v_mov_b32_e32 v110, 0
	v_mov_b32_e32 v111, 0
	v_mov_b32_e32 v104, 0
	v_mov_b32_e32 v105, 0
	v_mov_b32_e32 v106, 0
	v_mov_b32_e32 v107, 0
	v_mov_b32_e32 v100, 0
	v_mov_b32_e32 v101, 0
	v_mov_b32_e32 v102, 0
	v_mov_b32_e32 v103, 0
	v_mov_b32_e32 v225, 0
	s_waitcnt lgkmcnt(0)
	s_barrier
	s_mov_b32 s20, 64
	s_mov_b32 s88, 0x8000
	s_lshl_b32 s21, s20, 16
	s_add_u32 s21, s21, s61
	s_lshl_b32 s22, s20, 7
	s_add_u32 s22, s22, s62
	s_add_u32 m0, s88, s84
	s_add_u32 s86, s88, s84
	s_add_u32 s86, s86, 0x2000
	buffer_load_dwordx4 v235, s[24:27], s21 offen lds
	s_mov_b32 m0, s86
	s_nop 0
	buffer_load_dwordx4 v250, s[40:43], s22 offen lds
	s_mov_b32 s20, 65
	s_mov_b32 s88, 0xc000
	s_lshl_b32 s21, s20, 16
	s_add_u32 s21, s21, s61
	s_lshl_b32 s22, s20, 7
	s_add_u32 s22, s22, s62
	s_add_u32 m0, s88, s84
	s_add_u32 s86, s88, s84
	s_add_u32 s86, s86, 0x2000
	buffer_load_dwordx4 v235, s[24:27], s21 offen lds
	s_mov_b32 m0, s86
	s_nop 0
	buffer_load_dwordx4 v250, s[40:43], s22 offen lds
	s_mov_b32 s20, 66
	s_mov_b32 s88, 0x10000
	s_lshl_b32 s21, s20, 16
	s_add_u32 s21, s21, s61
	s_lshl_b32 s22, s20, 7
	s_add_u32 s22, s22, s62
	s_add_u32 m0, s88, s84
	s_add_u32 s86, s88, s84
	s_add_u32 s86, s86, 0x2000
	buffer_load_dwordx4 v235, s[24:27], s21 offen lds
	s_mov_b32 m0, s86
	s_nop 0
	buffer_load_dwordx4 v250, s[40:43], s22 offen lds
	s_mov_b32 s20, 67
	s_mov_b32 s88, 0x14000
	s_lshl_b32 s21, s20, 16
	s_add_u32 s21, s21, s61
	s_lshl_b32 s22, s20, 7
	s_add_u32 s22, s22, s62
	s_add_u32 m0, s88, s84
	s_add_u32 s86, s88, s84
	s_add_u32 s86, s86, 0x2000
	buffer_load_dwordx4 v235, s[24:27], s21 offen lds
	s_mov_b32 m0, s86
	s_nop 0
	buffer_load_dwordx4 v250, s[40:43], s22 offen lds
	v_sub_f32_e32 v204, v204, v239
	v_sub_f32_e32 v205, v205, v239
	v_sub_f32_e32 v206, v206, v239
	v_sub_f32_e32 v207, v207, v239
	v_sub_f32_e32 v208, v208, v239
	v_sub_f32_e32 v209, v209, v239
	v_sub_f32_e32 v210, v210, v239
	v_sub_f32_e32 v211, v211, v239
	v_cndmask_b32_e64 v204, v238, v204, s[0:1]
	v_cndmask_b32_e64 v205, v238, v205, s[6:7]
	v_cndmask_b32_e64 v206, v238, v206, s[8:9]
	v_cndmask_b32_e64 v207, v238, v207, s[10:11]
	v_cndmask_b32_e64 v208, v238, v208, s[12:13]
	v_cndmask_b32_e64 v209, v238, v209, s[14:15]
	v_cndmask_b32_e64 v210, v238, v210, s[16:17]
	v_cndmask_b32_e64 v211, v238, v211, s[18:19]
	v_sub_f32_e32 v80, v80, v239
	v_sub_f32_e32 v81, v81, v239
	v_sub_f32_e32 v82, v82, v239
	v_sub_f32_e32 v83, v83, v239
	v_sub_f32_e32 v84, v84, v239
	v_sub_f32_e32 v85, v85, v239
	v_sub_f32_e32 v86, v86, v239
	v_sub_f32_e32 v87, v87, v239
	v_cndmask_b32_e64 v80, v238, v80, s[0:1]
	v_cndmask_b32_e64 v81, v238, v81, s[6:7]
	v_cndmask_b32_e64 v82, v238, v82, s[8:9]
	v_cndmask_b32_e64 v83, v238, v83, s[10:11]
	v_cndmask_b32_e64 v84, v238, v84, s[12:13]
	v_cndmask_b32_e64 v85, v238, v85, s[14:15]
	v_cndmask_b32_e64 v86, v238, v86, s[16:17]
	v_cndmask_b32_e64 v87, v238, v87, s[18:19]
	v_sub_f32_e32 v180, v180, v239
	v_sub_f32_e32 v181, v181, v239
	v_sub_f32_e32 v182, v182, v239
	v_sub_f32_e32 v183, v183, v239
	v_sub_f32_e32 v184, v184, v239
	v_sub_f32_e32 v185, v185, v239
	v_sub_f32_e32 v186, v186, v239
	v_sub_f32_e32 v187, v187, v239
	v_cndmask_b32_e64 v180, v238, v180, s[0:1]
	v_cndmask_b32_e64 v181, v238, v181, s[6:7]
	v_cndmask_b32_e64 v182, v238, v182, s[8:9]
	v_cndmask_b32_e64 v183, v238, v183, s[10:11]
	v_cndmask_b32_e64 v184, v238, v184, s[12:13]
	v_cndmask_b32_e64 v185, v238, v185, s[14:15]
	v_cndmask_b32_e64 v186, v238, v186, s[16:17]
	v_cndmask_b32_e64 v187, v238, v187, s[18:19]
	v_sub_f32_e32 v212, v212, v239
	v_sub_f32_e32 v213, v213, v239
	v_sub_f32_e32 v214, v214, v239
	v_sub_f32_e32 v215, v215, v239
	v_sub_f32_e32 v242, v242, v239
	v_sub_f32_e32 v243, v243, v239
	v_sub_f32_e32 v244, v244, v239
	v_sub_f32_e32 v245, v245, v239
	v_cndmask_b32_e64 v212, v238, v212, s[0:1]
	v_cndmask_b32_e64 v213, v238, v213, s[6:7]
	v_cndmask_b32_e64 v214, v238, v214, s[8:9]
	v_cndmask_b32_e64 v215, v238, v215, s[10:11]
	v_cndmask_b32_e64 v242, v238, v242, s[12:13]
	v_cndmask_b32_e64 v243, v238, v243, s[14:15]
	v_cndmask_b32_e64 v244, v238, v244, s[16:17]
	v_cndmask_b32_e64 v245, v238, v245, s[18:19]
	v_add_u32_e32 v240, 0x400, v240
	s_mov_b32 s92, -1
	s_mov_b32 s63, 2
	s_waitcnt vmcnt(0) lgkmcnt(0)
	s_barrier
	s_add_u32 s92, s92, 1
	s_add_u32 s63, s63, 1
	s_cmp_eq_u32 s63, 3
	s_cselect_b32 s63, 0, s63
	s_lshl_b32 s95, s63, 14
	s_lshr_b32 s20, s63, 1
	s_lshl_b32 s20, s20, 4
	s_add_u32 s95, s95, s20
	s_add_u32 s95, s95, 0x18000
	s_sub_i32 s21, s92, s60
	s_sub_i32 s22, s92, s76
	s_cmp_lt_i32 s21, 0
	s_cselect_b32 s22, s92, s22
	s_max_i32 s22, s22, 0
	s_min_i32 s22, s22, 7
	s_lshr_b32 s86, s22, 1
	s_lshl_b32 s86, s86, 14
	s_add_u32 s86, s86, 0x8000
	s_and_b32 s88, s22, 1
	s_lshl_b32 s20, s88, 8
	s_add_u32 s23, s86, s20
	s_lshl_b32 s20, s88, 10
	s_add_u32 s33, s86, s20
	s_add_u32 s33, s33, 0x2000
	s_cmp_ge_i32 s21, 0
	s_cselect_b32 s20, 1, 0
	s_cmp_lt_i32 s21, s76
	s_cselect_b32 s20, s20, 0
	s_cmp_lg_u32 s20, 0
	s_cbranch_scc0 .Latt_cs2
	s_add_u32 s23, s95, s97
	s_add_u32 s33, s95, s90
.Latt_cs2:
	v_add_u32_e32 v251, s23, v233
	v_add_u32_e32 v253, s33, v234
	ds_read_b128 v[176:179], v251 offset:0
	ds_read_b128 v[168:171], v251 offset:4096
	ds_read_b128 v[172:175], v251 offset:2048
	ds_read_b128 v[164:167], v251 offset:6144
	ds_read_b128 v[32:35], v253 offset:0
	ds_read_b128 v[28:31], v253 offset:2048
	ds_read_b128 v[24:27], v253 offset:4096
	ds_read_b128 v[20:23], v253 offset:6144
	s_mov_b32 s94, 0
	s_cmp_eq_u32 s60, 0
	s_cbranch_scc1 .Latt_went
	s_mov_b32 s94, 1
	s_mov_b32 s91, 4
	s_branch .Latt_CA
.Latt_went:
	s_mov_b32 s94, 0
	s_cmp_eq_u32 s76, 8
	s_cbranch_scc1 .Latt_n8
	s_waitcnt lgkmcnt(0)
	s_waitcnt vmcnt(2)
	s_barrier
	s_add_u32 s20, s92, 3
	s_cmp_ge_u32 s20, s80
	s_cbranch_scc1 .Latt_sk3
	s_add_u32 s20, s20, s93
	s_lshl_b32 s21, s20, 16
	s_add_u32 s21, s21, s61
	s_lshl_b32 s22, s20, 7
	s_add_u32 s22, s22, s62
	s_add_u32 m0, s95, s84
	s_add_u32 s86, s95, s84
	s_add_u32 s86, s86, 0x2000
	buffer_load_dwordx4 v235, s[24:27], s21 offen lds
	s_mov_b32 m0, s86
	s_nop 0
	buffer_load_dwordx4 v250, s[40:43], s22 offen lds
.Latt_sk3:
	s_add_u32 s92, s92, 1
	s_add_u32 s63, s63, 1
	s_cmp_eq_u32 s63, 3
	s_cselect_b32 s63, 0, s63
	s_lshl_b32 s95, s63, 14
	s_lshr_b32 s20, s63, 1
	s_lshl_b32 s20, s20, 4
	s_add_u32 s95, s95, s20
	s_add_u32 s95, s95, 0x18000
	s_sub_i32 s21, s92, s60
	s_sub_i32 s22, s92, s76
	s_cmp_lt_i32 s21, 0
	s_cselect_b32 s22, s92, s22
	s_max_i32 s22, s22, 0
	s_min_i32 s22, s22, 7
	s_lshr_b32 s86, s22, 1
	s_lshl_b32 s86, s86, 14
	s_add_u32 s86, s86, 0x8000
	s_and_b32 s88, s22, 1
	s_lshl_b32 s20, s88, 8
	s_add_u32 s23, s86, s20
	s_lshl_b32 s20, s88, 10
	s_add_u32 s33, s86, s20
	s_add_u32 s33, s33, 0x2000
	s_cmp_ge_i32 s21, 0
	s_cselect_b32 s20, 1, 0
	s_cmp_lt_i32 s21, s76
	s_cselect_b32 s20, s20, 0
	s_cmp_lg_u32 s20, 0
	s_cbranch_scc0 .Latt_cs4
	s_add_u32 s23, s95, s97
	s_add_u32 s33, s95, s90
.Latt_cs4:
	v_add_u32_e32 v251, s23, v233
	v_add_u32_e32 v253, s33, v234
	ds_read_b128 v[48:51], v251 offset:0
	ds_read_b128 v[40:43], v251 offset:4096
	ds_read_b128 v[44:47], v251 offset:2048
	ds_read_b128 v[36:39], v251 offset:6144
	ds_read_b128 v[16:19], v253 offset:0
	ds_read_b128 v[12:15], v253 offset:2048
	ds_read_b128 v[8:11], v253 offset:4096
	ds_read_b128 v[4:7], v253 offset:6144
	ds_read2_b32 v[212:213], v240 offset0:0 offset1:1
	ds_read2_b32 v[214:215], v240 offset0:2 offset1:3
	ds_read2_b32 v[242:243], v240 offset0:4 offset1:5
	ds_read2_b32 v[244:245], v240 offset0:6 offset1:7
	v_mfma_f32_16x16x32_bf16 v[188:191], v[176:179], v[132:135], v[204:207]
	v_mfma_f32_16x16x32_bf16 v[192:195], v[168:171], v[132:135], v[208:211]
	v_mfma_f32_16x16x32_bf16 v[188:191], v[172:175], v[136:139], v[188:191]
	v_mfma_f32_16x16x32_bf16 v[192:195], v[164:167], v[136:139], v[192:195]
	s_nop 6
	v_exp_f32_e32 v188, v188
	v_exp_f32_e32 v189, v189
	v_exp_f32_e32 v190, v190
	v_exp_f32_e32 v191, v191
	v_exp_f32_e32 v192, v192
	v_exp_f32_e32 v193, v193
	v_exp_f32_e32 v194, v194
	v_exp_f32_e32 v195, v195
	v_cvt_pk_bf16_f32 v246, v188, v189
	v_cvt_pk_bf16_f32 v247, v190, v191
	v_cvt_pk_bf16_f32 v248, v192, v193
	v_cvt_pk_bf16_f32 v249, v194, v195
	v_add_f32_e32 v188, v188, v189
	v_add_f32_e32 v190, v190, v191
	v_add_f32_e32 v192, v192, v193
	v_add_f32_e32 v194, v194, v195
	v_add_f32_e32 v188, v188, v190
	v_add_f32_e32 v192, v192, v194
	v_add_f32_e32 v188, v188, v192
	v_add_f32_e32 v222, v222, v188
	s_waitcnt lgkmcnt(0)
	v_sub_f32_e32 v212, v212, v239
	v_sub_f32_e32 v213, v213, v239
	v_sub_f32_e32 v214, v214, v239
	v_mfma_f32_16x16x32_bf16 v[96:99], v[32:35], v[246:249], v[96:99]
	v_sub_f32_e32 v215, v215, v239
	v_sub_f32_e32 v242, v242, v239
	v_sub_f32_e32 v243, v243, v239
	v_mfma_f32_16x16x32_bf16 v[88:91], v[28:31], v[246:249], v[88:91]
	v_sub_f32_e32 v244, v244, v239
	v_sub_f32_e32 v245, v245, v239
	v_cndmask_b32_e64 v212, v238, v212, s[0:1]
	v_mfma_f32_16x16x32_bf16 v[72:75], v[24:27], v[246:249], v[72:75]
	v_cndmask_b32_e64 v213, v238, v213, s[6:7]
	v_cndmask_b32_e64 v214, v238, v214, s[8:9]
	v_cndmask_b32_e64 v215, v238, v215, s[10:11]
	v_mfma_f32_16x16x32_bf16 v[68:71], v[20:23], v[246:249], v[68:71]
	v_cndmask_b32_e64 v242, v238, v242, s[12:13]
	v_cndmask_b32_e64 v243, v238, v243, s[14:15]
	v_cndmask_b32_e64 v244, v238, v244, s[16:17]
	v_cndmask_b32_e64 v245, v238, v245, s[18:19]
	v_add_u32_e32 v240, 0x100, v240
	s_waitcnt lgkmcnt(0)
	s_waitcnt vmcnt(2)
	s_barrier
	s_add_u32 s20, s92, 3
	s_cmp_ge_u32 s20, s80
	s_cbranch_scc1 .Latt_sk5
	s_add_u32 s20, s20, s93
	s_lshl_b32 s21, s20, 16
	s_add_u32 s21, s21, s61
	s_lshl_b32 s22, s20, 7
	s_add_u32 s22, s22, s62
	s_add_u32 m0, s95, s84
	s_add_u32 s86, s95, s84
	s_add_u32 s86, s86, 0x2000
	buffer_load_dwordx4 v235, s[24:27], s21 offen lds
	s_mov_b32 m0, s86
	s_nop 0
	buffer_load_dwordx4 v250, s[40:43], s22 offen lds

.Latt_cs6:
	v_add_u32_e32 v251, s23, v233
	v_add_u32_e32 v253, s33, v234
	ds_read_b128 v[176:179], v251 offset:0
	ds_read_b128 v[168:171], v251 offset:4096
	ds_read_b128 v[172:175], v251 offset:2048
	ds_read_b128 v[164:167], v251 offset:6144
	ds_read_b128 v[32:35], v253 offset:0
	ds_read_b128 v[28:31], v253 offset:2048
	ds_read_b128 v[24:27], v253 offset:4096
	ds_read_b128 v[20:23], v253 offset:6144
	ds_read2_b32 v[180:181], v240 offset0:0 offset1:1
	ds_read2_b32 v[182:183], v240 offset0:2 offset1:3
	ds_read2_b32 v[184:185], v240 offset0:4 offset1:5
	ds_read2_b32 v[186:187], v240 offset0:6 offset1:7
	v_mfma_f32_16x16x32_bf16 v[188:191], v[48:51], v[140:143], v[204:207]
	v_mfma_f32_16x16x32_bf16 v[192:195], v[40:43], v[140:143], v[208:211]
	v_mfma_f32_16x16x32_bf16 v[188:191], v[44:47], v[144:147], v[188:191]
	v_mfma_f32_16x16x32_bf16 v[192:195], v[36:39], v[144:147], v[192:195]
	v_mfma_f32_16x16x32_bf16 v[196:199], v[48:51], v[132:135], v[212:215]
	v_mfma_f32_16x16x32_bf16 v[200:203], v[40:43], v[132:135], v[242:245]
	v_mfma_f32_16x16x32_bf16 v[196:199], v[44:47], v[136:139], v[196:199]
	v_mfma_f32_16x16x32_bf16 v[200:203], v[36:39], v[136:139], v[200:203]
	s_nop 2
	v_exp_f32_e32 v188, v188
	v_exp_f32_e32 v189, v189
	v_exp_f32_e32 v190, v190
	v_exp_f32_e32 v191, v191
	v_exp_f32_e32 v192, v192
	v_exp_f32_e32 v193, v193
	v_exp_f32_e32 v194, v194
	v_exp_f32_e32 v195, v195
	v_cvt_pk_bf16_f32 v246, v188, v189
	v_cvt_pk_bf16_f32 v247, v190, v191
	v_cvt_pk_bf16_f32 v248, v192, v193
	v_cvt_pk_bf16_f32 v249, v194, v195
	v_add_f32_e32 v188, v188, v189
	v_add_f32_e32 v190, v190, v191
	v_add_f32_e32 v192, v192, v193
	v_add_f32_e32 v194, v194, v195
	v_add_f32_e32 v188, v188, v190
	v_add_f32_e32 v192, v192, v194
	v_add_f32_e32 v188, v188, v192
	v_add_f32_e32 v223, v223, v188
	v_exp_f32_e32 v196, v196
	v_exp_f32_e32 v197, v197
	v_exp_f32_e32 v198, v198
	v_exp_f32_e32 v199, v199
	v_mfma_f32_16x16x32_bf16 v[64:67], v[16:19], v[246:249], v[64:67]
	v_exp_f32_e32 v200, v200
	v_exp_f32_e32 v201, v201
	v_exp_f32_e32 v202, v202
	v_exp_f32_e32 v203, v203
	v_mfma_f32_16x16x32_bf16 v[60:63], v[12:15], v[246:249], v[60:63]
	v_cvt_pk_bf16_f32 v92, v196, v197
	v_cvt_pk_bf16_f32 v93, v198, v199
	v_cvt_pk_bf16_f32 v94, v200, v201
	v_cvt_pk_bf16_f32 v95, v202, v203
	v_mfma_f32_16x16x32_bf16 v[56:59], v[8:11], v[246:249], v[56:59]
	v_add_f32_e32 v196, v196, v197
	v_add_f32_e32 v198, v198, v199
	v_add_f32_e32 v200, v200, v201
	v_add_f32_e32 v202, v202, v203
	v_mfma_f32_16x16x32_bf16 v[52:55], v[4:7], v[246:249], v[52:55]
	v_add_f32_e32 v196, v196, v198
	v_add_f32_e32 v200, v200, v202
	v_add_f32_e32 v196, v196, v200
	v_add_f32_e32 v222, v222, v196
	s_waitcnt lgkmcnt(0)
	v_sub_f32_e32 v180, v180, v239
	v_sub_f32_e32 v181, v181, v239
	v_sub_f32_e32 v182, v182, v239
	v_mfma_f32_16x16x32_bf16 v[96:99], v[16:19], v[92:95], v[96:99]
	v_sub_f32_e32 v183, v183, v239
	v_sub_f32_e32 v184, v184, v239
	v_sub_f32_e32 v185, v185, v239
	v_mfma_f32_16x16x32_bf16 v[88:91], v[12:15], v[92:95], v[88:91]
	v_sub_f32_e32 v186, v186, v239
	v_sub_f32_e32 v187, v187, v239
	v_cndmask_b32_e64 v180, v238, v180, s[0:1]
	v_mfma_f32_16x16x32_bf16 v[72:75], v[8:11], v[92:95], v[72:75]
	v_cndmask_b32_e64 v181, v238, v181, s[6:7]
	v_cndmask_b32_e64 v182, v238, v182, s[8:9]
	v_cndmask_b32_e64 v183, v238, v183, s[10:11]
	v_mfma_f32_16x16x32_bf16 v[68:71], v[4:7], v[92:95], v[68:71]
	v_cndmask_b32_e64 v184, v238, v184, s[12:13]
	v_cndmask_b32_e64 v185, v238, v185, s[14:15]
	v_cndmask_b32_e64 v186, v238, v186, s[16:17]
	v_cndmask_b32_e64 v187, v238, v187, s[18:19]
	v_add_u32_e32 v240, 0x100, v240
	s_waitcnt lgkmcnt(0)
	s_waitcnt vmcnt(2)
	s_barrier
	s_add_u32 s20, s92, 3
	s_cmp_ge_u32 s20, s80
	s_cbranch_scc1 .Latt_sk7
	s_add_u32 s20, s20, s93
	s_lshl_b32 s21, s20, 16
	s_add_u32 s21, s21, s61
	s_lshl_b32 s22, s20, 7
	s_add_u32 s22, s22, s62
	s_add_u32 m0, s95, s84
	s_add_u32 s86, s95, s84
	s_add_u32 s86, s86, 0x2000
	buffer_load_dwordx4 v235, s[24:27], s21 offen lds
	s_mov_b32 m0, s86
	s_nop 0
	buffer_load_dwordx4 v250, s[40:43], s22 offen lds

.Latt_cs8:
	v_add_u32_e32 v251, s23, v233
	v_add_u32_e32 v253, s33, v234
	ds_read_b128 v[48:51], v251 offset:0
	ds_read_b128 v[40:43], v251 offset:4096
	ds_read_b128 v[44:47], v251 offset:2048
	ds_read_b128 v[36:39], v251 offset:6144
	ds_read_b128 v[16:19], v253 offset:0
	ds_read_b128 v[12:15], v253 offset:2048
	ds_read_b128 v[8:11], v253 offset:4096
	ds_read_b128 v[4:7], v253 offset:6144
	ds_read2_b32 v[80:81], v240 offset0:0 offset1:1
	ds_read2_b32 v[82:83], v240 offset0:2 offset1:3
	ds_read2_b32 v[84:85], v240 offset0:4 offset1:5
	ds_read2_b32 v[86:87], v240 offset0:6 offset1:7
	v_mfma_f32_16x16x32_bf16 v[188:191], v[176:179], v[148:151], v[204:207]
	v_mfma_f32_16x16x32_bf16 v[192:195], v[168:171], v[148:151], v[208:211]
	v_mfma_f32_16x16x32_bf16 v[188:191], v[172:175], v[152:155], v[188:191]
	v_mfma_f32_16x16x32_bf16 v[192:195], v[164:167], v[152:155], v[192:195]
	v_mfma_f32_16x16x32_bf16 v[196:199], v[176:179], v[140:143], v[212:215]
	v_mfma_f32_16x16x32_bf16 v[200:203], v[168:171], v[140:143], v[242:245]
	v_mfma_f32_16x16x32_bf16 v[196:199], v[172:175], v[144:147], v[196:199]
	v_mfma_f32_16x16x32_bf16 v[200:203], v[164:167], v[144:147], v[200:203]
	s_nop 2
	v_exp_f32_e32 v188, v188
	v_exp_f32_e32 v189, v189
	v_exp_f32_e32 v190, v190
	v_exp_f32_e32 v191, v191
	v_exp_f32_e32 v192, v192
	v_exp_f32_e32 v193, v193
	v_exp_f32_e32 v194, v194
	v_exp_f32_e32 v195, v195
	v_cvt_pk_bf16_f32 v246, v188, v189
	v_cvt_pk_bf16_f32 v247, v190, v191
	v_cvt_pk_bf16_f32 v248, v192, v193
	v_cvt_pk_bf16_f32 v249, v194, v195
	v_add_f32_e32 v188, v188, v189
	v_add_f32_e32 v190, v190, v191
	v_add_f32_e32 v192, v192, v193
	v_add_f32_e32 v194, v194, v195
	v_add_f32_e32 v188, v188, v190
	v_add_f32_e32 v192, v192, v194
	v_add_f32_e32 v188, v188, v192
	v_add_f32_e32 v224, v224, v188
	v_mfma_f32_16x16x32_bf16 v[188:191], v[176:179], v[132:135], v[180:183]
	v_mfma_f32_16x16x32_bf16 v[192:195], v[168:171], v[132:135], v[184:187]
	v_mfma_f32_16x16x32_bf16 v[188:191], v[172:175], v[136:139], v[188:191]
	v_mfma_f32_16x16x32_bf16 v[192:195], v[164:167], v[136:139], v[192:195]
	v_exp_f32_e32 v196, v196
	v_exp_f32_e32 v197, v197
	v_exp_f32_e32 v198, v198
	v_exp_f32_e32 v199, v199
	v_mfma_f32_16x16x32_bf16 v[128:131], v[32:35], v[246:249], v[128:131]
	v_exp_f32_e32 v200, v200
	v_exp_f32_e32 v201, v201
	v_exp_f32_e32 v202, v202
	v_exp_f32_e32 v203, v203
	v_mfma_f32_16x16x32_bf16 v[124:127], v[28:31], v[246:249], v[124:127]
	v_cvt_pk_bf16_f32 v92, v196, v197
	v_cvt_pk_bf16_f32 v93, v198, v199
	v_cvt_pk_bf16_f32 v94, v200, v201
	v_cvt_pk_bf16_f32 v95, v202, v203
	v_mfma_f32_16x16x32_bf16 v[120:123], v[24:27], v[246:249], v[120:123]
	v_add_f32_e32 v196, v196, v197
	v_add_f32_e32 v198, v198, v199
	v_add_f32_e32 v200, v200, v201
	v_add_f32_e32 v202, v202, v203
	v_mfma_f32_16x16x32_bf16 v[116:119], v[20:23], v[246:249], v[116:119]
	v_add_f32_e32 v196, v196, v198
	v_add_f32_e32 v200, v200, v202
	v_add_f32_e32 v196, v196, v200
	v_add_f32_e32 v223, v223, v196
	v_exp_f32_e32 v188, v188
	v_exp_f32_e32 v189, v189
	v_exp_f32_e32 v190, v190
	v_exp_f32_e32 v191, v191
	v_mfma_f32_16x16x32_bf16 v[64:67], v[32:35], v[92:95], v[64:67]
	v_exp_f32_e32 v192, v192
	v_exp_f32_e32 v193, v193
	v_exp_f32_e32 v194, v194
	v_exp_f32_e32 v195, v195
	v_mfma_f32_16x16x32_bf16 v[60:63], v[28:31], v[92:95], v[60:63]
	v_cvt_pk_bf16_f32 v246, v188, v189
	v_cvt_pk_bf16_f32 v247, v190, v191
	v_cvt_pk_bf16_f32 v248, v192, v193
	v_cvt_pk_bf16_f32 v249, v194, v195
	v_mfma_f32_16x16x32_bf16 v[56:59], v[24:27], v[92:95], v[56:59]
	v_add_f32_e32 v188, v188, v189
	v_add_f32_e32 v190, v190, v191
	v_add_f32_e32 v192, v192, v193
	v_add_f32_e32 v194, v194, v195
	v_mfma_f32_16x16x32_bf16 v[52:55], v[20:23], v[92:95], v[52:55]
	v_add_f32_e32 v188, v188, v190
	v_add_f32_e32 v192, v192, v194
	v_add_f32_e32 v188, v188, v192
	v_add_f32_e32 v222, v222, v188
	s_waitcnt lgkmcnt(0)
	v_sub_f32_e32 v80, v80, v239
	v_sub_f32_e32 v81, v81, v239
	v_sub_f32_e32 v82, v82, v239
	v_mfma_f32_16x16x32_bf16 v[96:99], v[32:35], v[246:249], v[96:99]
	v_sub_f32_e32 v83, v83, v239
	v_sub_f32_e32 v84, v84, v239
	v_sub_f32_e32 v85, v85, v239
	v_mfma_f32_16x16x32_bf16 v[88:91], v[28:31], v[246:249], v[88:91]
	v_sub_f32_e32 v86, v86, v239
	v_sub_f32_e32 v87, v87, v239
	v_cndmask_b32_e64 v80, v238, v80, s[0:1]
	v_mfma_f32_16x16x32_bf16 v[72:75], v[24:27], v[246:249], v[72:75]
	v_cndmask_b32_e64 v81, v238, v81, s[6:7]
	v_cndmask_b32_e64 v82, v238, v82, s[8:9]
	v_cndmask_b32_e64 v83, v238, v83, s[10:11]
	v_mfma_f32_16x16x32_bf16 v[68:71], v[20:23], v[246:249], v[68:71]
	v_cndmask_b32_e64 v84, v238, v84, s[12:13]
	v_cndmask_b32_e64 v85, v238, v85, s[14:15]
	v_cndmask_b32_e64 v86, v238, v86, s[16:17]
	v_cndmask_b32_e64 v87, v238, v87, s[18:19]
	v_add_u32_e32 v240, 0x100, v240
	s_waitcnt lgkmcnt(0)
	s_waitcnt vmcnt(2)
	s_barrier
	s_add_u32 s20, s92, 3
	s_cmp_ge_u32 s20, s80
	s_cbranch_scc1 .Latt_sk9
	s_add_u32 s20, s20, s93
	s_lshl_b32 s21, s20, 16
	s_add_u32 s21, s21, s61
	s_lshl_b32 s22, s20, 7
	s_add_u32 s22, s22, s62
	s_add_u32 m0, s95, s84
	s_add_u32 s86, s95, s84
	s_add_u32 s86, s86, 0x2000
	buffer_load_dwordx4 v235, s[24:27], s21 offen lds
	s_mov_b32 m0, s86
	s_nop 0
	buffer_load_dwordx4 v250, s[40:43], s22 offen lds

.Latt_cs10:
	v_add_u32_e32 v251, s23, v233
	v_add_u32_e32 v253, s33, v234
	ds_read_b128 v[176:179], v251 offset:0
	ds_read_b128 v[168:171], v251 offset:4096
	ds_read_b128 v[172:175], v251 offset:2048
	ds_read_b128 v[164:167], v251 offset:6144
	ds_read_b128 v[32:35], v253 offset:0
	ds_read_b128 v[28:31], v253 offset:2048
	ds_read_b128 v[24:27], v253 offset:4096
	ds_read_b128 v[20:23], v253 offset:6144
	v_mfma_f32_16x16x32_bf16 v[188:191], v[48:51], v[156:159], v[204:207]
	v_mfma_f32_16x16x32_bf16 v[192:195], v[40:43], v[156:159], v[208:211]
	v_mfma_f32_16x16x32_bf16 v[188:191], v[44:47], v[160:163], v[188:191]
	v_mfma_f32_16x16x32_bf16 v[192:195], v[36:39], v[160:163], v[192:195]
	ds_read2_b32 v[204:205], v240 offset0:0 offset1:1
	ds_read2_b32 v[206:207], v240 offset0:2 offset1:3
	ds_read2_b32 v[208:209], v240 offset0:4 offset1:5
	ds_read2_b32 v[210:211], v240 offset0:6 offset1:7
	v_mfma_f32_16x16x32_bf16 v[196:199], v[48:51], v[148:151], v[212:215]
	v_mfma_f32_16x16x32_bf16 v[200:203], v[40:43], v[148:151], v[242:245]
	v_mfma_f32_16x16x32_bf16 v[196:199], v[44:47], v[152:155], v[196:199]
	v_mfma_f32_16x16x32_bf16 v[200:203], v[36:39], v[152:155], v[200:203]
	v_exp_f32_e32 v188, v188
	v_exp_f32_e32 v189, v189
	v_exp_f32_e32 v190, v190
	v_exp_f32_e32 v191, v191
	v_exp_f32_e32 v192, v192
	v_exp_f32_e32 v193, v193
	v_exp_f32_e32 v194, v194
	v_exp_f32_e32 v195, v195
	v_cvt_pk_bf16_f32 v246, v188, v189
	v_cvt_pk_bf16_f32 v247, v190, v191
	v_cvt_pk_bf16_f32 v248, v192, v193
	v_cvt_pk_bf16_f32 v249, v194, v195
	v_add_f32_e32 v188, v188, v189
	v_add_f32_e32 v190, v190, v191
	v_add_f32_e32 v192, v192, v193
	v_add_f32_e32 v194, v194, v195
	v_add_f32_e32 v188, v188, v190
	v_add_f32_e32 v192, v192, v194
	v_add_f32_e32 v188, v188, v192
	v_add_f32_e32 v225, v225, v188
	v_mfma_f32_16x16x32_bf16 v[188:191], v[48:51], v[140:143], v[180:183]
	v_mfma_f32_16x16x32_bf16 v[192:195], v[40:43], v[140:143], v[184:187]
	v_mfma_f32_16x16x32_bf16 v[188:191], v[44:47], v[144:147], v[188:191]
	v_mfma_f32_16x16x32_bf16 v[192:195], v[36:39], v[144:147], v[192:195]
	v_exp_f32_e32 v196, v196
	v_exp_f32_e32 v197, v197
	v_exp_f32_e32 v198, v198
	v_exp_f32_e32 v199, v199
	v_mfma_f32_16x16x32_bf16 v[112:115], v[16:19], v[246:249], v[112:115]
	v_exp_f32_e32 v200, v200
	v_exp_f32_e32 v201, v201
	v_exp_f32_e32 v202, v202
	v_exp_f32_e32 v203, v203
	v_mfma_f32_16x16x32_bf16 v[108:111], v[12:15], v[246:249], v[108:111]
	v_cvt_pk_bf16_f32 v92, v196, v197
	v_cvt_pk_bf16_f32 v93, v198, v199
	v_cvt_pk_bf16_f32 v94, v200, v201
	v_cvt_pk_bf16_f32 v95, v202, v203
	v_mfma_f32_16x16x32_bf16 v[104:107], v[8:11], v[246:249], v[104:107]
	v_add_f32_e32 v196, v196, v197
	v_add_f32_e32 v198, v198, v199
	v_add_f32_e32 v200, v200, v201
	v_add_f32_e32 v202, v202, v203
	v_mfma_f32_16x16x32_bf16 v[100:103], v[4:7], v[246:249], v[100:103]
	v_add_f32_e32 v196, v196, v198
	v_add_f32_e32 v200, v200, v202
	v_add_f32_e32 v196, v196, v200
	v_add_f32_e32 v224, v224, v196
	v_mfma_f32_16x16x32_bf16 v[196:199], v[48:51], v[132:135], v[80:83]
	v_mfma_f32_16x16x32_bf16 v[200:203], v[40:43], v[132:135], v[84:87]
	v_mfma_f32_16x16x32_bf16 v[196:199], v[44:47], v[136:139], v[196:199]
	v_mfma_f32_16x16x32_bf16 v[200:203], v[36:39], v[136:139], v[200:203]
	v_exp_f32_e32 v188, v188
	v_exp_f32_e32 v189, v189
	v_exp_f32_e32 v190, v190
	v_exp_f32_e32 v191, v191
	v_mfma_f32_16x16x32_bf16 v[128:131], v[16:19], v[92:95], v[128:131]
	v_exp_f32_e32 v192, v192
	v_exp_f32_e32 v193, v193
	v_exp_f32_e32 v194, v194
	v_exp_f32_e32 v195, v195
	v_mfma_f32_16x16x32_bf16 v[124:127], v[12:15], v[92:95], v[124:127]
	v_cvt_pk_bf16_f32 v246, v188, v189
	v_cvt_pk_bf16_f32 v247, v190, v191
	v_cvt_pk_bf16_f32 v248, v192, v193
	v_cvt_pk_bf16_f32 v249, v194, v195
	v_mfma_f32_16x16x32_bf16 v[120:123], v[8:11], v[92:95], v[120:123]
	v_add_f32_e32 v188, v188, v189
	v_add_f32_e32 v190, v190, v191
	v_add_f32_e32 v192, v192, v193
	v_add_f32_e32 v194, v194, v195
	v_mfma_f32_16x16x32_bf16 v[116:119], v[4:7], v[92:95], v[116:119]
	v_add_f32_e32 v188, v188, v190
	v_add_f32_e32 v192, v192, v194
	v_add_f32_e32 v188, v188, v192
	v_add_f32_e32 v223, v223, v188
	v_exp_f32_e32 v196, v196
	v_exp_f32_e32 v197, v197
	v_exp_f32_e32 v198, v198
	v_exp_f32_e32 v199, v199
	v_mfma_f32_16x16x32_bf16 v[64:67], v[16:19], v[246:249], v[64:67]
	v_exp_f32_e32 v200, v200
	v_exp_f32_e32 v201, v201
	v_exp_f32_e32 v202, v202
	v_exp_f32_e32 v203, v203
	v_mfma_f32_16x16x32_bf16 v[60:63], v[12:15], v[246:249], v[60:63]
	v_cvt_pk_bf16_f32 v92, v196, v197
	v_cvt_pk_bf16_f32 v93, v198, v199
	v_cvt_pk_bf16_f32 v94, v200, v201
	v_cvt_pk_bf16_f32 v95, v202, v203
	v_mfma_f32_16x16x32_bf16 v[56:59], v[8:11], v[246:249], v[56:59]
	v_add_f32_e32 v196, v196, v197
	v_add_f32_e32 v198, v198, v199
	v_add_f32_e32 v200, v200, v201
	v_add_f32_e32 v202, v202, v203
	v_mfma_f32_16x16x32_bf16 v[52:55], v[4:7], v[246:249], v[52:55]
	v_add_f32_e32 v196, v196, v198
	v_add_f32_e32 v200, v200, v202
	v_add_f32_e32 v196, v196, v200
	v_add_f32_e32 v222, v222, v196
	s_waitcnt lgkmcnt(0)
	v_sub_f32_e32 v204, v204, v239
	v_sub_f32_e32 v205, v205, v239
	v_sub_f32_e32 v206, v206, v239
	v_mfma_f32_16x16x32_bf16 v[96:99], v[16:19], v[92:95], v[96:99]
	v_sub_f32_e32 v207, v207, v239
	v_sub_f32_e32 v208, v208, v239
	v_sub_f32_e32 v209, v209, v239
	v_mfma_f32_16x16x32_bf16 v[88:91], v[12:15], v[92:95], v[88:91]
	v_sub_f32_e32 v210, v210, v239
	v_sub_f32_e32 v211, v211, v239
	v_cndmask_b32_e64 v204, v238, v204, s[0:1]
	v_mfma_f32_16x16x32_bf16 v[72:75], v[8:11], v[92:95], v[72:75]
	v_cndmask_b32_e64 v205, v238, v205, s[6:7]
	v_cndmask_b32_e64 v206, v238, v206, s[8:9]
	v_cndmask_b32_e64 v207, v238, v207, s[10:11]
	v_mfma_f32_16x16x32_bf16 v[68:71], v[4:7], v[92:95], v[68:71]
	v_cndmask_b32_e64 v208, v238, v208, s[12:13]
	v_cndmask_b32_e64 v209, v238, v209, s[14:15]
	v_cndmask_b32_e64 v210, v238, v210, s[16:17]
	v_cndmask_b32_e64 v211, v238, v211, s[18:19]
	v_add_u32_e32 v240, 0x100, v240
	s_waitcnt lgkmcnt(0)
	s_waitcnt vmcnt(2)
	s_barrier
	s_add_u32 s20, s92, 3
	s_cmp_ge_u32 s20, s80
	s_cbranch_scc1 .Latt_sk11
	s_add_u32 s20, s20, s93
	s_lshl_b32 s21, s20, 16
	s_add_u32 s21, s21, s61
	s_lshl_b32 s22, s20, 7
	s_add_u32 s22, s22, s62
	s_add_u32 m0, s95, s84
	s_add_u32 s86, s95, s84
	s_add_u32 s86, s86, 0x2000
	buffer_load_dwordx4 v235, s[24:27], s21 offen lds
	s_mov_b32 m0, s86
	s_nop 0
	buffer_load_dwordx4 v250, s[40:43], s22 offen lds

.Latt_cs12:
	v_add_u32_e32 v251, s23, v233
	v_add_u32_e32 v253, s33, v234
	ds_read_b128 v[48:51], v251 offset:0
	ds_read_b128 v[40:43], v251 offset:4096
	ds_read_b128 v[44:47], v251 offset:2048
	ds_read_b128 v[36:39], v251 offset:6144
	ds_read_b128 v[16:19], v253 offset:0
	ds_read_b128 v[12:15], v253 offset:2048
	ds_read_b128 v[8:11], v253 offset:4096
	ds_read_b128 v[4:7], v253 offset:6144
	v_mfma_f32_16x16x32_bf16 v[188:191], v[176:179], v[156:159], v[212:215]
	v_mfma_f32_16x16x32_bf16 v[192:195], v[168:171], v[156:159], v[242:245]
	v_mfma_f32_16x16x32_bf16 v[188:191], v[172:175], v[160:163], v[188:191]
	v_mfma_f32_16x16x32_bf16 v[192:195], v[164:167], v[160:163], v[192:195]
	ds_read2_b32 v[212:213], v240 offset0:0 offset1:1
	ds_read2_b32 v[214:215], v240 offset0:2 offset1:3
	ds_read2_b32 v[242:243], v240 offset0:4 offset1:5
	ds_read2_b32 v[244:245], v240 offset0:6 offset1:7
	v_mfma_f32_16x16x32_bf16 v[196:199], v[176:179], v[148:151], v[180:183]
	v_mfma_f32_16x16x32_bf16 v[200:203], v[168:171], v[148:151], v[184:187]
	v_mfma_f32_16x16x32_bf16 v[196:199], v[172:175], v[152:155], v[196:199]
	v_mfma_f32_16x16x32_bf16 v[200:203], v[164:167], v[152:155], v[200:203]
	v_exp_f32_e32 v188, v188
	v_exp_f32_e32 v189, v189
	v_exp_f32_e32 v190, v190
	v_exp_f32_e32 v191, v191
	v_exp_f32_e32 v192, v192
	v_exp_f32_e32 v193, v193
	v_exp_f32_e32 v194, v194
	v_exp_f32_e32 v195, v195
	v_cvt_pk_bf16_f32 v246, v188, v189
	v_cvt_pk_bf16_f32 v247, v190, v191
	v_cvt_pk_bf16_f32 v248, v192, v193
	v_cvt_pk_bf16_f32 v249, v194, v195
	v_add_f32_e32 v188, v188, v189
	v_add_f32_e32 v190, v190, v191
	v_add_f32_e32 v192, v192, v193
	v_add_f32_e32 v194, v194, v195
	v_add_f32_e32 v188, v188, v190
	v_add_f32_e32 v192, v192, v194
	v_add_f32_e32 v188, v188, v192
	v_add_f32_e32 v225, v225, v188
	v_mfma_f32_16x16x32_bf16 v[188:191], v[176:179], v[140:143], v[80:83]
	v_mfma_f32_16x16x32_bf16 v[192:195], v[168:171], v[140:143], v[84:87]
	v_mfma_f32_16x16x32_bf16 v[188:191], v[172:175], v[144:147], v[188:191]
	v_mfma_f32_16x16x32_bf16 v[192:195], v[164:167], v[144:147], v[192:195]
	v_exp_f32_e32 v196, v196
	v_exp_f32_e32 v197, v197
	v_exp_f32_e32 v198, v198
	v_exp_f32_e32 v199, v199
	v_mfma_f32_16x16x32_bf16 v[112:115], v[32:35], v[246:249], v[112:115]
	v_exp_f32_e32 v200, v200
	v_exp_f32_e32 v201, v201
	v_exp_f32_e32 v202, v202
	v_exp_f32_e32 v203, v203
	v_mfma_f32_16x16x32_bf16 v[108:111], v[28:31], v[246:249], v[108:111]
	v_cvt_pk_bf16_f32 v92, v196, v197
	v_cvt_pk_bf16_f32 v93, v198, v199
	v_cvt_pk_bf16_f32 v94, v200, v201
	v_cvt_pk_bf16_f32 v95, v202, v203
	v_mfma_f32_16x16x32_bf16 v[104:107], v[24:27], v[246:249], v[104:107]
	v_add_f32_e32 v196, v196, v197
	v_add_f32_e32 v198, v198, v199
	v_add_f32_e32 v200, v200, v201
	v_add_f32_e32 v202, v202, v203
	v_mfma_f32_16x16x32_bf16 v[100:103], v[20:23], v[246:249], v[100:103]
	v_add_f32_e32 v196, v196, v198
	v_add_f32_e32 v200, v200, v202
	v_add_f32_e32 v196, v196, v200
	v_add_f32_e32 v224, v224, v196
	v_mfma_f32_16x16x32_bf16 v[196:199], v[176:179], v[132:135], v[204:207]
	v_mfma_f32_16x16x32_bf16 v[200:203], v[168:171], v[132:135], v[208:211]
	v_mfma_f32_16x16x32_bf16 v[196:199], v[172:175], v[136:139], v[196:199]
	v_mfma_f32_16x16x32_bf16 v[200:203], v[164:167], v[136:139], v[200:203]
	v_exp_f32_e32 v188, v188
	v_exp_f32_e32 v189, v189
	v_exp_f32_e32 v190, v190
	v_exp_f32_e32 v191, v191
	v_mfma_f32_16x16x32_bf16 v[128:131], v[32:35], v[92:95], v[128:131]
	v_exp_f32_e32 v192, v192
	v_exp_f32_e32 v193, v193
	v_exp_f32_e32 v194, v194
	v_exp_f32_e32 v195, v195
	v_mfma_f32_16x16x32_bf16 v[124:127], v[28:31], v[92:95], v[124:127]
	v_cvt_pk_bf16_f32 v246, v188, v189
	v_cvt_pk_bf16_f32 v247, v190, v191
	v_cvt_pk_bf16_f32 v248, v192, v193
	v_cvt_pk_bf16_f32 v249, v194, v195
	v_mfma_f32_16x16x32_bf16 v[120:123], v[24:27], v[92:95], v[120:123]
	v_add_f32_e32 v188, v188, v189
	v_add_f32_e32 v190, v190, v191
	v_add_f32_e32 v192, v192, v193
	v_add_f32_e32 v194, v194, v195
	v_mfma_f32_16x16x32_bf16 v[116:119], v[20:23], v[92:95], v[116:119]
	v_add_f32_e32 v188, v188, v190
	v_add_f32_e32 v192, v192, v194
	v_add_f32_e32 v188, v188, v192
	v_add_f32_e32 v223, v223, v188
	v_exp_f32_e32 v196, v196
	v_exp_f32_e32 v197, v197
	v_exp_f32_e32 v198, v198
	v_exp_f32_e32 v199, v199
	v_mfma_f32_16x16x32_bf16 v[64:67], v[32:35], v[246:249], v[64:67]
	v_exp_f32_e32 v200, v200
	v_exp_f32_e32 v201, v201
	v_exp_f32_e32 v202, v202
	v_exp_f32_e32 v203, v203
	v_mfma_f32_16x16x32_bf16 v[60:63], v[28:31], v[246:249], v[60:63]
	v_cvt_pk_bf16_f32 v92, v196, v197
	v_cvt_pk_bf16_f32 v93, v198, v199
	v_cvt_pk_bf16_f32 v94, v200, v201
	v_cvt_pk_bf16_f32 v95, v202, v203
	v_mfma_f32_16x16x32_bf16 v[56:59], v[24:27], v[246:249], v[56:59]
	v_add_f32_e32 v196, v196, v197
	v_add_f32_e32 v198, v198, v199
	v_add_f32_e32 v200, v200, v201
	v_add_f32_e32 v202, v202, v203
	v_mfma_f32_16x16x32_bf16 v[52:55], v[20:23], v[246:249], v[52:55]
	v_add_f32_e32 v196, v196, v198
	v_add_f32_e32 v200, v200, v202
	v_add_f32_e32 v196, v196, v200
	v_add_f32_e32 v222, v222, v196
	s_waitcnt lgkmcnt(0)
	v_sub_f32_e32 v212, v212, v239
	v_sub_f32_e32 v213, v213, v239
	v_sub_f32_e32 v214, v214, v239
	v_mfma_f32_16x16x32_bf16 v[96:99], v[32:35], v[92:95], v[96:99]
	v_sub_f32_e32 v215, v215, v239
	v_sub_f32_e32 v242, v242, v239
	v_sub_f32_e32 v243, v243, v239
	v_mfma_f32_16x16x32_bf16 v[88:91], v[28:31], v[92:95], v[88:91]
	v_sub_f32_e32 v244, v244, v239
	v_sub_f32_e32 v245, v245, v239
	v_cndmask_b32_e64 v212, v238, v212, s[0:1]
	v_mfma_f32_16x16x32_bf16 v[72:75], v[24:27], v[92:95], v[72:75]
	v_cndmask_b32_e64 v213, v238, v213, s[6:7]
	v_cndmask_b32_e64 v214, v238, v214, s[8:9]
	v_cndmask_b32_e64 v215, v238, v215, s[10:11]
	v_mfma_f32_16x16x32_bf16 v[68:71], v[20:23], v[92:95], v[68:71]
	v_cndmask_b32_e64 v242, v238, v242, s[12:13]
	v_cndmask_b32_e64 v243, v238, v243, s[14:15]
	v_cndmask_b32_e64 v244, v238, v244, s[16:17]
	v_cndmask_b32_e64 v245, v238, v245, s[18:19]
	v_add_u32_e32 v240, 0x100, v240
	s_waitcnt lgkmcnt(0)
	s_waitcnt vmcnt(2)
	s_barrier
	s_add_u32 s20, s92, 3
	s_cmp_ge_u32 s20, s80
	s_cbranch_scc1 .Latt_sk13
	s_add_u32 s20, s20, s93
	s_lshl_b32 s21, s20, 16
	s_add_u32 s21, s21, s61
	s_lshl_b32 s22, s20, 7
	s_add_u32 s22, s22, s62
	s_add_u32 m0, s95, s84
	s_add_u32 s86, s95, s84
	s_add_u32 s86, s86, 0x2000
	buffer_load_dwordx4 v235, s[24:27], s21 offen lds
	s_mov_b32 m0, s86
	s_nop 0
	buffer_load_dwordx4 v250, s[40:43], s22 offen lds

.Latt_cs14:
	v_add_u32_e32 v251, s23, v233
	v_add_u32_e32 v253, s33, v234
	ds_read_b128 v[176:179], v251 offset:0
	ds_read_b128 v[168:171], v251 offset:4096
	ds_read_b128 v[172:175], v251 offset:2048
	ds_read_b128 v[164:167], v251 offset:6144
	ds_read_b128 v[32:35], v253 offset:0
	ds_read_b128 v[28:31], v253 offset:2048
	ds_read_b128 v[24:27], v253 offset:4096
	ds_read_b128 v[20:23], v253 offset:6144
	v_mfma_f32_16x16x32_bf16 v[188:191], v[48:51], v[156:159], v[180:183]
	v_mfma_f32_16x16x32_bf16 v[192:195], v[40:43], v[156:159], v[184:187]
	v_mfma_f32_16x16x32_bf16 v[188:191], v[44:47], v[160:163], v[188:191]
	v_mfma_f32_16x16x32_bf16 v[192:195], v[36:39], v[160:163], v[192:195]
	ds_read2_b32 v[180:181], v240 offset0:0 offset1:1
	ds_read2_b32 v[182:183], v240 offset0:2 offset1:3
	ds_read2_b32 v[184:185], v240 offset0:4 offset1:5
	ds_read2_b32 v[186:187], v240 offset0:6 offset1:7
	v_mfma_f32_16x16x32_bf16 v[196:199], v[48:51], v[148:151], v[80:83]
	v_mfma_f32_16x16x32_bf16 v[200:203], v[40:43], v[148:151], v[84:87]
	v_mfma_f32_16x16x32_bf16 v[196:199], v[44:47], v[152:155], v[196:199]
	v_mfma_f32_16x16x32_bf16 v[200:203], v[36:39], v[152:155], v[200:203]
	v_exp_f32_e32 v188, v188
	v_exp_f32_e32 v189, v189
	v_exp_f32_e32 v190, v190
	v_exp_f32_e32 v191, v191
	v_exp_f32_e32 v192, v192
	v_exp_f32_e32 v193, v193
	v_exp_f32_e32 v194, v194
	v_exp_f32_e32 v195, v195
	v_cvt_pk_bf16_f32 v246, v188, v189
	v_cvt_pk_bf16_f32 v247, v190, v191
	v_cvt_pk_bf16_f32 v248, v192, v193
	v_cvt_pk_bf16_f32 v249, v194, v195
	v_add_f32_e32 v188, v188, v189
	v_add_f32_e32 v190, v190, v191
	v_add_f32_e32 v192, v192, v193
	v_add_f32_e32 v194, v194, v195
	v_add_f32_e32 v188, v188, v190
	v_add_f32_e32 v192, v192, v194
	v_add_f32_e32 v188, v188, v192
	v_add_f32_e32 v225, v225, v188
	v_mfma_f32_16x16x32_bf16 v[188:191], v[48:51], v[140:143], v[204:207]
	v_mfma_f32_16x16x32_bf16 v[192:195], v[40:43], v[140:143], v[208:211]
	v_mfma_f32_16x16x32_bf16 v[188:191], v[44:47], v[144:147], v[188:191]
	v_mfma_f32_16x16x32_bf16 v[192:195], v[36:39], v[144:147], v[192:195]
	v_exp_f32_e32 v196, v196
	v_exp_f32_e32 v197, v197
	v_exp_f32_e32 v198, v198
	v_exp_f32_e32 v199, v199
	v_mfma_f32_16x16x32_bf16 v[112:115], v[16:19], v[246:249], v[112:115]
	v_exp_f32_e32 v200, v200
	v_exp_f32_e32 v201, v201
	v_exp_f32_e32 v202, v202
	v_exp_f32_e32 v203, v203
	v_mfma_f32_16x16x32_bf16 v[108:111], v[12:15], v[246:249], v[108:111]
	v_cvt_pk_bf16_f32 v92, v196, v197
	v_cvt_pk_bf16_f32 v93, v198, v199
	v_cvt_pk_bf16_f32 v94, v200, v201
	v_cvt_pk_bf16_f32 v95, v202, v203
	v_mfma_f32_16x16x32_bf16 v[104:107], v[8:11], v[246:249], v[104:107]
	v_add_f32_e32 v196, v196, v197
	v_add_f32_e32 v198, v198, v199
	v_add_f32_e32 v200, v200, v201
	v_add_f32_e32 v202, v202, v203
	v_mfma_f32_16x16x32_bf16 v[100:103], v[4:7], v[246:249], v[100:103]
	v_add_f32_e32 v196, v196, v198
	v_add_f32_e32 v200, v200, v202
	v_add_f32_e32 v196, v196, v200
	v_add_f32_e32 v224, v224, v196
	v_mfma_f32_16x16x32_bf16 v[196:199], v[48:51], v[132:135], v[212:215]
	v_mfma_f32_16x16x32_bf16 v[200:203], v[40:43], v[132:135], v[242:245]
	v_mfma_f32_16x16x32_bf16 v[196:199], v[44:47], v[136:139], v[196:199]
	v_mfma_f32_16x16x32_bf16 v[200:203], v[36:39], v[136:139], v[200:203]
	v_exp_f32_e32 v188, v188
	v_exp_f32_e32 v189, v189
	v_exp_f32_e32 v190, v190
	v_exp_f32_e32 v191, v191
	v_mfma_f32_16x16x32_bf16 v[128:131], v[16:19], v[92:95], v[128:131]
	v_exp_f32_e32 v192, v192
	v_exp_f32_e32 v193, v193
	v_exp_f32_e32 v194, v194
	v_exp_f32_e32 v195, v195
	v_mfma_f32_16x16x32_bf16 v[124:127], v[12:15], v[92:95], v[124:127]
	v_cvt_pk_bf16_f32 v246, v188, v189
	v_cvt_pk_bf16_f32 v247, v190, v191
	v_cvt_pk_bf16_f32 v248, v192, v193
	v_cvt_pk_bf16_f32 v249, v194, v195
	v_mfma_f32_16x16x32_bf16 v[120:123], v[8:11], v[92:95], v[120:123]
	v_add_f32_e32 v188, v188, v189
	v_add_f32_e32 v190, v190, v191
	v_add_f32_e32 v192, v192, v193
	v_add_f32_e32 v194, v194, v195
	v_mfma_f32_16x16x32_bf16 v[116:119], v[4:7], v[92:95], v[116:119]
	v_add_f32_e32 v188, v188, v190
	v_add_f32_e32 v192, v192, v194
	v_add_f32_e32 v188, v188, v192
	v_add_f32_e32 v223, v223, v188
	v_exp_f32_e32 v196, v196
	v_exp_f32_e32 v197, v197
	v_exp_f32_e32 v198, v198
	v_exp_f32_e32 v199, v199
	v_mfma_f32_16x16x32_bf16 v[64:67], v[16:19], v[246:249], v[64:67]
	v_exp_f32_e32 v200, v200
	v_exp_f32_e32 v201, v201
	v_exp_f32_e32 v202, v202
	v_exp_f32_e32 v203, v203
	v_mfma_f32_16x16x32_bf16 v[60:63], v[12:15], v[246:249], v[60:63]
	v_cvt_pk_bf16_f32 v92, v196, v197
	v_cvt_pk_bf16_f32 v93, v198, v199
	v_cvt_pk_bf16_f32 v94, v200, v201
	v_cvt_pk_bf16_f32 v95, v202, v203
	v_mfma_f32_16x16x32_bf16 v[56:59], v[8:11], v[246:249], v[56:59]
	v_add_f32_e32 v196, v196, v197
	v_add_f32_e32 v198, v198, v199
	v_add_f32_e32 v200, v200, v201
	v_add_f32_e32 v202, v202, v203
	v_mfma_f32_16x16x32_bf16 v[52:55], v[4:7], v[246:249], v[52:55]
	v_add_f32_e32 v196, v196, v198
	v_add_f32_e32 v200, v200, v202
	v_add_f32_e32 v196, v196, v200
	v_add_f32_e32 v222, v222, v196
	s_waitcnt lgkmcnt(0)
	v_sub_f32_e32 v180, v180, v239
	v_sub_f32_e32 v181, v181, v239
	v_sub_f32_e32 v182, v182, v239
	v_mfma_f32_16x16x32_bf16 v[96:99], v[16:19], v[92:95], v[96:99]
	v_sub_f32_e32 v183, v183, v239
	v_sub_f32_e32 v184, v184, v239
	v_sub_f32_e32 v185, v185, v239
	v_mfma_f32_16x16x32_bf16 v[88:91], v[12:15], v[92:95], v[88:91]
	v_sub_f32_e32 v186, v186, v239
	v_sub_f32_e32 v187, v187, v239
	v_cndmask_b32_e64 v180, v238, v180, s[0:1]
	v_mfma_f32_16x16x32_bf16 v[72:75], v[8:11], v[92:95], v[72:75]
	v_cndmask_b32_e64 v181, v238, v181, s[6:7]
	v_cndmask_b32_e64 v182, v238, v182, s[8:9]
	v_cndmask_b32_e64 v183, v238, v183, s[10:11]
	v_mfma_f32_16x16x32_bf16 v[68:71], v[4:7], v[92:95], v[68:71]
	v_cndmask_b32_e64 v184, v238, v184, s[12:13]
	v_cndmask_b32_e64 v185, v238, v185, s[14:15]
	v_cndmask_b32_e64 v186, v238, v186, s[16:17]
	v_cndmask_b32_e64 v187, v238, v187, s[18:19]
	v_add_u32_e32 v240, 0x100, v240
	s_waitcnt lgkmcnt(0)
	s_waitcnt vmcnt(2)
	s_barrier
	s_add_u32 s20, s92, 3
	s_cmp_ge_u32 s20, s80
	s_cbranch_scc1 .Latt_sk15
	s_add_u32 s20, s20, s93
	s_lshl_b32 s21, s20, 16
	s_add_u32 s21, s21, s61
	s_lshl_b32 s22, s20, 7
	s_add_u32 s22, s22, s62
	s_add_u32 m0, s95, s84
	s_add_u32 s86, s95, s84
	s_add_u32 s86, s86, 0x2000
	buffer_load_dwordx4 v235, s[24:27], s21 offen lds
	s_mov_b32 m0, s86
	s_nop 0
	buffer_load_dwordx4 v250, s[40:43], s22 offen lds

.Latt_cs16:
	v_add_u32_e32 v251, s23, v233
	v_add_u32_e32 v253, s33, v234
	ds_read_b128 v[48:51], v251 offset:0
	ds_read_b128 v[40:43], v251 offset:4096
	ds_read_b128 v[44:47], v251 offset:2048
	ds_read_b128 v[36:39], v251 offset:6144
	ds_read_b128 v[16:19], v253 offset:0
	ds_read_b128 v[12:15], v253 offset:2048
	ds_read_b128 v[8:11], v253 offset:4096
	ds_read_b128 v[4:7], v253 offset:6144
	v_mfma_f32_16x16x32_bf16 v[188:191], v[176:179], v[156:159], v[80:83]
	v_mfma_f32_16x16x32_bf16 v[192:195], v[168:171], v[156:159], v[84:87]
	v_mfma_f32_16x16x32_bf16 v[188:191], v[172:175], v[160:163], v[188:191]
	v_mfma_f32_16x16x32_bf16 v[192:195], v[164:167], v[160:163], v[192:195]
	ds_read2_b32 v[80:81], v240 offset0:0 offset1:1
	ds_read2_b32 v[82:83], v240 offset0:2 offset1:3
	ds_read2_b32 v[84:85], v240 offset0:4 offset1:5
	ds_read2_b32 v[86:87], v240 offset0:6 offset1:7
	v_mfma_f32_16x16x32_bf16 v[196:199], v[176:179], v[148:151], v[204:207]
	v_mfma_f32_16x16x32_bf16 v[200:203], v[168:171], v[148:151], v[208:211]
	v_mfma_f32_16x16x32_bf16 v[196:199], v[172:175], v[152:155], v[196:199]
	v_mfma_f32_16x16x32_bf16 v[200:203], v[164:167], v[152:155], v[200:203]
	v_exp_f32_e32 v188, v188
	v_exp_f32_e32 v189, v189
	v_exp_f32_e32 v190, v190
	v_exp_f32_e32 v191, v191
	v_exp_f32_e32 v192, v192
	v_exp_f32_e32 v193, v193
	v_exp_f32_e32 v194, v194
	v_exp_f32_e32 v195, v195
	v_cvt_pk_bf16_f32 v246, v188, v189
	v_cvt_pk_bf16_f32 v247, v190, v191
	v_cvt_pk_bf16_f32 v248, v192, v193
	v_cvt_pk_bf16_f32 v249, v194, v195
	v_add_f32_e32 v188, v188, v189
	v_add_f32_e32 v190, v190, v191
	v_add_f32_e32 v192, v192, v193
	v_add_f32_e32 v194, v194, v195
	v_add_f32_e32 v188, v188, v190
	v_add_f32_e32 v192, v192, v194
	v_add_f32_e32 v188, v188, v192
	v_add_f32_e32 v225, v225, v188
	v_mfma_f32_16x16x32_bf16 v[188:191], v[176:179], v[140:143], v[212:215]
	v_mfma_f32_16x16x32_bf16 v[192:195], v[168:171], v[140:143], v[242:245]
	v_mfma_f32_16x16x32_bf16 v[188:191], v[172:175], v[144:147], v[188:191]
	v_mfma_f32_16x16x32_bf16 v[192:195], v[164:167], v[144:147], v[192:195]
	v_exp_f32_e32 v196, v196
	v_exp_f32_e32 v197, v197
	v_exp_f32_e32 v198, v198
	v_exp_f32_e32 v199, v199
	v_mfma_f32_16x16x32_bf16 v[112:115], v[32:35], v[246:249], v[112:115]
	v_exp_f32_e32 v200, v200
	v_exp_f32_e32 v201, v201
	v_exp_f32_e32 v202, v202
	v_exp_f32_e32 v203, v203
	v_mfma_f32_16x16x32_bf16 v[108:111], v[28:31], v[246:249], v[108:111]
	v_cvt_pk_bf16_f32 v92, v196, v197
	v_cvt_pk_bf16_f32 v93, v198, v199
	v_cvt_pk_bf16_f32 v94, v200, v201
	v_cvt_pk_bf16_f32 v95, v202, v203
	v_mfma_f32_16x16x32_bf16 v[104:107], v[24:27], v[246:249], v[104:107]
	v_add_f32_e32 v196, v196, v197
	v_add_f32_e32 v198, v198, v199
	v_add_f32_e32 v200, v200, v201
	v_add_f32_e32 v202, v202, v203
	v_mfma_f32_16x16x32_bf16 v[100:103], v[20:23], v[246:249], v[100:103]
	v_add_f32_e32 v196, v196, v198
	v_add_f32_e32 v200, v200, v202
	v_add_f32_e32 v196, v196, v200
	v_add_f32_e32 v224, v224, v196
	v_mfma_f32_16x16x32_bf16 v[196:199], v[176:179], v[132:135], v[180:183]
	v_mfma_f32_16x16x32_bf16 v[200:203], v[168:171], v[132:135], v[184:187]
	v_mfma_f32_16x16x32_bf16 v[196:199], v[172:175], v[136:139], v[196:199]
	v_mfma_f32_16x16x32_bf16 v[200:203], v[164:167], v[136:139], v[200:203]
	v_exp_f32_e32 v188, v188
	v_exp_f32_e32 v189, v189
	v_exp_f32_e32 v190, v190
	v_exp_f32_e32 v191, v191
	v_mfma_f32_16x16x32_bf16 v[128:131], v[32:35], v[92:95], v[128:131]
	v_exp_f32_e32 v192, v192
	v_exp_f32_e32 v193, v193
	v_exp_f32_e32 v194, v194
	v_exp_f32_e32 v195, v195
	v_mfma_f32_16x16x32_bf16 v[124:127], v[28:31], v[92:95], v[124:127]
	v_cvt_pk_bf16_f32 v246, v188, v189
	v_cvt_pk_bf16_f32 v247, v190, v191
	v_cvt_pk_bf16_f32 v248, v192, v193
	v_cvt_pk_bf16_f32 v249, v194, v195
	v_mfma_f32_16x16x32_bf16 v[120:123], v[24:27], v[92:95], v[120:123]
	v_add_f32_e32 v188, v188, v189
	v_add_f32_e32 v190, v190, v191
	v_add_f32_e32 v192, v192, v193
	v_add_f32_e32 v194, v194, v195
	v_mfma_f32_16x16x32_bf16 v[116:119], v[20:23], v[92:95], v[116:119]
	v_add_f32_e32 v188, v188, v190
	v_add_f32_e32 v192, v192, v194
	v_add_f32_e32 v188, v188, v192
	v_add_f32_e32 v223, v223, v188
	v_exp_f32_e32 v196, v196
	v_exp_f32_e32 v197, v197
	v_exp_f32_e32 v198, v198
	v_exp_f32_e32 v199, v199
	v_mfma_f32_16x16x32_bf16 v[64:67], v[32:35], v[246:249], v[64:67]
	v_exp_f32_e32 v200, v200
	v_exp_f32_e32 v201, v201
	v_exp_f32_e32 v202, v202
	v_exp_f32_e32 v203, v203
	v_mfma_f32_16x16x32_bf16 v[60:63], v[28:31], v[246:249], v[60:63]
	v_cvt_pk_bf16_f32 v92, v196, v197
	v_cvt_pk_bf16_f32 v93, v198, v199
	v_cvt_pk_bf16_f32 v94, v200, v201
	v_cvt_pk_bf16_f32 v95, v202, v203
	v_mfma_f32_16x16x32_bf16 v[56:59], v[24:27], v[246:249], v[56:59]
	v_add_f32_e32 v196, v196, v197
	v_add_f32_e32 v198, v198, v199
	v_add_f32_e32 v200, v200, v201
	v_add_f32_e32 v202, v202, v203
	v_mfma_f32_16x16x32_bf16 v[52:55], v[20:23], v[246:249], v[52:55]
	v_add_f32_e32 v196, v196, v198
	v_add_f32_e32 v200, v200, v202
	v_add_f32_e32 v196, v196, v200
	v_add_f32_e32 v222, v222, v196
	s_waitcnt lgkmcnt(0)
	v_sub_f32_e32 v80, v80, v239
	v_sub_f32_e32 v81, v81, v239
	v_sub_f32_e32 v82, v82, v239
	v_mfma_f32_16x16x32_bf16 v[96:99], v[32:35], v[92:95], v[96:99]
	v_sub_f32_e32 v83, v83, v239
	v_sub_f32_e32 v84, v84, v239
	v_sub_f32_e32 v85, v85, v239
	v_mfma_f32_16x16x32_bf16 v[88:91], v[28:31], v[92:95], v[88:91]
	v_sub_f32_e32 v86, v86, v239
	v_sub_f32_e32 v87, v87, v239
	v_cndmask_b32_e64 v80, v238, v80, s[0:1]
	v_mfma_f32_16x16x32_bf16 v[72:75], v[24:27], v[92:95], v[72:75]
	v_cndmask_b32_e64 v81, v238, v81, s[6:7]
	v_cndmask_b32_e64 v82, v238, v82, s[8:9]
	v_cndmask_b32_e64 v83, v238, v83, s[10:11]
	v_mfma_f32_16x16x32_bf16 v[68:71], v[20:23], v[92:95], v[68:71]
	v_cndmask_b32_e64 v84, v238, v84, s[12:13]
	v_cndmask_b32_e64 v85, v238, v85, s[14:15]
	v_cndmask_b32_e64 v86, v238, v86, s[16:17]
	v_cndmask_b32_e64 v87, v238, v87, s[18:19]
	v_add_u32_e32 v240, 0x100, v240
	s_waitcnt lgkmcnt(0)
	s_waitcnt vmcnt(2)
	s_barrier
	s_add_u32 s20, s92, 3
	s_cmp_ge_u32 s20, s80
	s_cbranch_scc1 .Latt_sk17
	s_add_u32 s20, s20, s93
	s_lshl_b32 s21, s20, 16
	s_add_u32 s21, s21, s61
	s_lshl_b32 s22, s20, 7
	s_add_u32 s22, s22, s62
	s_add_u32 m0, s95, s84
	s_add_u32 s86, s95, s84
	s_add_u32 s86, s86, 0x2000
	buffer_load_dwordx4 v235, s[24:27], s21 offen lds
	s_mov_b32 m0, s86
	s_nop 0
	buffer_load_dwordx4 v250, s[40:43], s22 offen lds

.Latt_cs18:
	v_add_u32_e32 v251, s23, v233
	v_add_u32_e32 v253, s33, v234
	ds_read_b128 v[176:179], v251 offset:0
	ds_read_b128 v[168:171], v251 offset:4096
	ds_read_b128 v[172:175], v251 offset:2048
	ds_read_b128 v[164:167], v251 offset:6144
	ds_read_b128 v[32:35], v253 offset:0
	ds_read_b128 v[28:31], v253 offset:2048
	ds_read_b128 v[24:27], v253 offset:4096
	ds_read_b128 v[20:23], v253 offset:6144
	v_mfma_f32_16x16x32_bf16 v[188:191], v[48:51], v[156:159], v[204:207]
	v_mfma_f32_16x16x32_bf16 v[192:195], v[40:43], v[156:159], v[208:211]
	v_mfma_f32_16x16x32_bf16 v[188:191], v[44:47], v[160:163], v[188:191]
	v_mfma_f32_16x16x32_bf16 v[192:195], v[36:39], v[160:163], v[192:195]
	v_mfma_f32_16x16x32_bf16 v[196:199], v[48:51], v[148:151], v[212:215]
	v_mfma_f32_16x16x32_bf16 v[200:203], v[40:43], v[148:151], v[242:245]
	v_mfma_f32_16x16x32_bf16 v[196:199], v[44:47], v[152:155], v[196:199]
	v_mfma_f32_16x16x32_bf16 v[200:203], v[36:39], v[152:155], v[200:203]
	s_nop 2
	v_exp_f32_e32 v188, v188
	v_exp_f32_e32 v189, v189
	v_exp_f32_e32 v190, v190
	v_exp_f32_e32 v191, v191
	v_exp_f32_e32 v192, v192
	v_exp_f32_e32 v193, v193
	v_exp_f32_e32 v194, v194
	v_exp_f32_e32 v195, v195
	v_cvt_pk_bf16_f32 v246, v188, v189
	v_cvt_pk_bf16_f32 v247, v190, v191
	v_cvt_pk_bf16_f32 v248, v192, v193
	v_cvt_pk_bf16_f32 v249, v194, v195
	v_add_f32_e32 v188, v188, v189
	v_add_f32_e32 v190, v190, v191
	v_add_f32_e32 v192, v192, v193
	v_add_f32_e32 v194, v194, v195
	v_add_f32_e32 v188, v188, v190
	v_add_f32_e32 v192, v192, v194
	v_add_f32_e32 v188, v188, v192
	v_add_f32_e32 v225, v225, v188
	v_mfma_f32_16x16x32_bf16 v[188:191], v[48:51], v[140:143], v[180:183]
	v_mfma_f32_16x16x32_bf16 v[192:195], v[40:43], v[140:143], v[184:187]
	v_mfma_f32_16x16x32_bf16 v[188:191], v[44:47], v[144:147], v[188:191]
	v_mfma_f32_16x16x32_bf16 v[192:195], v[36:39], v[144:147], v[192:195]
	v_exp_f32_e32 v196, v196
	v_exp_f32_e32 v197, v197
	v_exp_f32_e32 v198, v198
	v_exp_f32_e32 v199, v199
	v_mfma_f32_16x16x32_bf16 v[112:115], v[16:19], v[246:249], v[112:115]
	v_exp_f32_e32 v200, v200
	v_exp_f32_e32 v201, v201
	v_exp_f32_e32 v202, v202
	v_exp_f32_e32 v203, v203
	v_mfma_f32_16x16x32_bf16 v[108:111], v[12:15], v[246:249], v[108:111]
	v_cvt_pk_bf16_f32 v92, v196, v197
	v_cvt_pk_bf16_f32 v93, v198, v199
	v_cvt_pk_bf16_f32 v94, v200, v201
	v_cvt_pk_bf16_f32 v95, v202, v203
	v_mfma_f32_16x16x32_bf16 v[104:107], v[8:11], v[246:249], v[104:107]
	v_add_f32_e32 v196, v196, v197
	v_add_f32_e32 v198, v198, v199
	v_add_f32_e32 v200, v200, v201
	v_add_f32_e32 v202, v202, v203
	v_mfma_f32_16x16x32_bf16 v[100:103], v[4:7], v[246:249], v[100:103]
	v_add_f32_e32 v196, v196, v198
	v_add_f32_e32 v200, v200, v202
	v_add_f32_e32 v196, v196, v200
	v_add_f32_e32 v224, v224, v196
	v_mfma_f32_16x16x32_bf16 v[196:199], v[48:51], v[132:135], v[80:83]
	v_mfma_f32_16x16x32_bf16 v[200:203], v[40:43], v[132:135], v[84:87]
	v_mfma_f32_16x16x32_bf16 v[196:199], v[44:47], v[136:139], v[196:199]
	v_mfma_f32_16x16x32_bf16 v[200:203], v[36:39], v[136:139], v[200:203]
	v_exp_f32_e32 v188, v188
	v_exp_f32_e32 v189, v189
	v_exp_f32_e32 v190, v190
	v_exp_f32_e32 v191, v191
	v_mfma_f32_16x16x32_bf16 v[128:131], v[16:19], v[92:95], v[128:131]
	v_exp_f32_e32 v192, v192
	v_exp_f32_e32 v193, v193
	v_exp_f32_e32 v194, v194
	v_exp_f32_e32 v195, v195
	v_mfma_f32_16x16x32_bf16 v[124:127], v[12:15], v[92:95], v[124:127]
	v_cvt_pk_bf16_f32 v246, v188, v189
	v_cvt_pk_bf16_f32 v247, v190, v191
	v_cvt_pk_bf16_f32 v248, v192, v193
	v_cvt_pk_bf16_f32 v249, v194, v195
	v_mfma_f32_16x16x32_bf16 v[120:123], v[8:11], v[92:95], v[120:123]
	v_add_f32_e32 v188, v188, v189
	v_add_f32_e32 v190, v190, v191
	v_add_f32_e32 v192, v192, v193
	v_add_f32_e32 v194, v194, v195
	v_mfma_f32_16x16x32_bf16 v[116:119], v[4:7], v[92:95], v[116:119]
	v_add_f32_e32 v188, v188, v190
	v_add_f32_e32 v192, v192, v194
	v_add_f32_e32 v188, v188, v192
	v_add_f32_e32 v223, v223, v188
	v_exp_f32_e32 v196, v196
	v_exp_f32_e32 v197, v197
	v_exp_f32_e32 v198, v198
	v_exp_f32_e32 v199, v199
	v_mfma_f32_16x16x32_bf16 v[64:67], v[16:19], v[246:249], v[64:67]
	v_exp_f32_e32 v200, v200
	v_exp_f32_e32 v201, v201
	v_exp_f32_e32 v202, v202
	v_exp_f32_e32 v203, v203
	v_mfma_f32_16x16x32_bf16 v[60:63], v[12:15], v[246:249], v[60:63]
	v_cvt_pk_bf16_f32 v92, v196, v197
	v_cvt_pk_bf16_f32 v93, v198, v199
	v_cvt_pk_bf16_f32 v94, v200, v201
	v_cvt_pk_bf16_f32 v95, v202, v203
	v_mfma_f32_16x16x32_bf16 v[56:59], v[8:11], v[246:249], v[56:59]
	v_add_f32_e32 v196, v196, v197
	v_add_f32_e32 v198, v198, v199
	v_add_f32_e32 v200, v200, v201
	v_add_f32_e32 v202, v202, v203
	v_mfma_f32_16x16x32_bf16 v[52:55], v[4:7], v[246:249], v[52:55]
	v_add_f32_e32 v196, v196, v198
	v_add_f32_e32 v200, v200, v202
	v_add_f32_e32 v196, v196, v200
	v_add_f32_e32 v222, v222, v196
	v_mfma_f32_16x16x32_bf16 v[96:99], v[16:19], v[92:95], v[96:99]
	v_mfma_f32_16x16x32_bf16 v[88:91], v[12:15], v[92:95], v[88:91]
	v_mfma_f32_16x16x32_bf16 v[72:75], v[8:11], v[92:95], v[72:75]
	v_mfma_f32_16x16x32_bf16 v[68:71], v[4:7], v[92:95], v[68:71]
	v_add_u32_e32 v240, 0x100, v240
	s_waitcnt lgkmcnt(0)
	s_waitcnt vmcnt(2)
	s_barrier
	s_add_u32 s20, s92, 3
	s_cmp_ge_u32 s20, s80
	s_cbranch_scc1 .Latt_sk19
	s_add_u32 s20, s20, s93
	s_lshl_b32 s21, s20, 16
	s_add_u32 s21, s21, s61
	s_lshl_b32 s22, s20, 7
	s_add_u32 s22, s22, s62
	s_add_u32 m0, s95, s84
	s_add_u32 s86, s95, s84
	s_add_u32 s86, s86, 0x2000
	buffer_load_dwordx4 v235, s[24:27], s21 offen lds
	s_mov_b32 m0, s86
	s_nop 0
	buffer_load_dwordx4 v250, s[40:43], s22 offen lds

.Latt_cs20:
	v_add_u32_e32 v251, s23, v233
	v_add_u32_e32 v253, s33, v234
	ds_read_b128 v[48:51], v251 offset:0
	ds_read_b128 v[40:43], v251 offset:4096
	ds_read_b128 v[44:47], v251 offset:2048
	ds_read_b128 v[36:39], v251 offset:6144
	ds_read_b128 v[16:19], v253 offset:0
	ds_read_b128 v[12:15], v253 offset:2048
	ds_read_b128 v[8:11], v253 offset:4096
	ds_read_b128 v[4:7], v253 offset:6144
	v_mfma_f32_16x16x32_bf16 v[188:191], v[176:179], v[156:159], v[212:215]
	v_mfma_f32_16x16x32_bf16 v[192:195], v[168:171], v[156:159], v[242:245]
	v_mfma_f32_16x16x32_bf16 v[188:191], v[172:175], v[160:163], v[188:191]
	v_mfma_f32_16x16x32_bf16 v[192:195], v[164:167], v[160:163], v[192:195]
	v_mfma_f32_16x16x32_bf16 v[196:199], v[176:179], v[148:151], v[180:183]
	v_mfma_f32_16x16x32_bf16 v[200:203], v[168:171], v[148:151], v[184:187]
	v_mfma_f32_16x16x32_bf16 v[196:199], v[172:175], v[152:155], v[196:199]
	v_mfma_f32_16x16x32_bf16 v[200:203], v[164:167], v[152:155], v[200:203]
	s_nop 2
	v_exp_f32_e32 v188, v188
	v_exp_f32_e32 v189, v189
	v_exp_f32_e32 v190, v190
	v_exp_f32_e32 v191, v191
	v_exp_f32_e32 v192, v192
	v_exp_f32_e32 v193, v193
	v_exp_f32_e32 v194, v194
	v_exp_f32_e32 v195, v195
	v_cvt_pk_bf16_f32 v246, v188, v189
	v_cvt_pk_bf16_f32 v247, v190, v191
	v_cvt_pk_bf16_f32 v248, v192, v193
	v_cvt_pk_bf16_f32 v249, v194, v195
	v_add_f32_e32 v188, v188, v189
	v_add_f32_e32 v190, v190, v191
	v_add_f32_e32 v192, v192, v193
	v_add_f32_e32 v194, v194, v195
	v_add_f32_e32 v188, v188, v190
	v_add_f32_e32 v192, v192, v194
	v_add_f32_e32 v188, v188, v192
	v_add_f32_e32 v225, v225, v188
	v_mfma_f32_16x16x32_bf16 v[188:191], v[176:179], v[140:143], v[80:83]
	v_mfma_f32_16x16x32_bf16 v[192:195], v[168:171], v[140:143], v[84:87]
	v_mfma_f32_16x16x32_bf16 v[188:191], v[172:175], v[144:147], v[188:191]
	v_mfma_f32_16x16x32_bf16 v[192:195], v[164:167], v[144:147], v[192:195]
	v_exp_f32_e32 v196, v196
	v_exp_f32_e32 v197, v197
	v_exp_f32_e32 v198, v198
	v_exp_f32_e32 v199, v199
	v_mfma_f32_16x16x32_bf16 v[112:115], v[32:35], v[246:249], v[112:115]
	v_exp_f32_e32 v200, v200
	v_exp_f32_e32 v201, v201
	v_exp_f32_e32 v202, v202
	v_exp_f32_e32 v203, v203
	v_mfma_f32_16x16x32_bf16 v[108:111], v[28:31], v[246:249], v[108:111]
	v_cvt_pk_bf16_f32 v92, v196, v197
	v_cvt_pk_bf16_f32 v93, v198, v199
	v_cvt_pk_bf16_f32 v94, v200, v201
	v_cvt_pk_bf16_f32 v95, v202, v203
	v_mfma_f32_16x16x32_bf16 v[104:107], v[24:27], v[246:249], v[104:107]
	v_add_f32_e32 v196, v196, v197
	v_add_f32_e32 v198, v198, v199
	v_add_f32_e32 v200, v200, v201
	v_add_f32_e32 v202, v202, v203
	v_mfma_f32_16x16x32_bf16 v[100:103], v[20:23], v[246:249], v[100:103]
	v_add_f32_e32 v196, v196, v198
	v_add_f32_e32 v200, v200, v202
	v_add_f32_e32 v196, v196, v200
	v_add_f32_e32 v224, v224, v196
	v_exp_f32_e32 v188, v188
	v_exp_f32_e32 v189, v189
	v_exp_f32_e32 v190, v190
	v_exp_f32_e32 v191, v191
	v_mfma_f32_16x16x32_bf16 v[128:131], v[32:35], v[92:95], v[128:131]
	v_exp_f32_e32 v192, v192
	v_exp_f32_e32 v193, v193
	v_exp_f32_e32 v194, v194
	v_exp_f32_e32 v195, v195
	v_mfma_f32_16x16x32_bf16 v[124:127], v[28:31], v[92:95], v[124:127]
	v_cvt_pk_bf16_f32 v246, v188, v189
	v_cvt_pk_bf16_f32 v247, v190, v191
	v_cvt_pk_bf16_f32 v248, v192, v193
	v_cvt_pk_bf16_f32 v249, v194, v195
	v_mfma_f32_16x16x32_bf16 v[120:123], v[24:27], v[92:95], v[120:123]
	v_add_f32_e32 v188, v188, v189
	v_add_f32_e32 v190, v190, v191
	v_add_f32_e32 v192, v192, v193
	v_add_f32_e32 v194, v194, v195
	v_mfma_f32_16x16x32_bf16 v[116:119], v[20:23], v[92:95], v[116:119]
	v_add_f32_e32 v188, v188, v190
	v_add_f32_e32 v192, v192, v194
	v_add_f32_e32 v188, v188, v192
	v_add_f32_e32 v223, v223, v188
	v_mfma_f32_16x16x32_bf16 v[64:67], v[32:35], v[246:249], v[64:67]
	v_mfma_f32_16x16x32_bf16 v[60:63], v[28:31], v[246:249], v[60:63]
	v_mfma_f32_16x16x32_bf16 v[56:59], v[24:27], v[246:249], v[56:59]
	v_mfma_f32_16x16x32_bf16 v[52:55], v[20:23], v[246:249], v[52:55]
	v_add_u32_e32 v240, 0x100, v240
	s_waitcnt lgkmcnt(0)
	s_waitcnt vmcnt(2)
	s_barrier
	s_add_u32 s20, s92, 3
	s_cmp_ge_u32 s20, s80
	s_cbranch_scc1 .Latt_sk21
	s_add_u32 s20, s20, s93
	s_lshl_b32 s21, s20, 16
	s_add_u32 s21, s21, s61
	s_lshl_b32 s22, s20, 7
	s_add_u32 s22, s22, s62
	s_add_u32 m0, s95, s84
	s_add_u32 s86, s95, s84
	s_add_u32 s86, s86, 0x2000
	buffer_load_dwordx4 v235, s[24:27], s21 offen lds
	s_mov_b32 m0, s86
	s_nop 0
	buffer_load_dwordx4 v250, s[40:43], s22 offen lds

.Latt_cs22:
	v_add_u32_e32 v251, s23, v233
	v_add_u32_e32 v253, s33, v234
	ds_read_b128 v[176:179], v251 offset:0
	ds_read_b128 v[168:171], v251 offset:4096
	ds_read_b128 v[172:175], v251 offset:2048
	ds_read_b128 v[164:167], v251 offset:6144
	ds_read_b128 v[32:35], v253 offset:0
	ds_read_b128 v[28:31], v253 offset:2048
	ds_read_b128 v[24:27], v253 offset:4096
	ds_read_b128 v[20:23], v253 offset:6144
	v_mfma_f32_16x16x32_bf16 v[188:191], v[48:51], v[156:159], v[180:183]
	v_mfma_f32_16x16x32_bf16 v[192:195], v[40:43], v[156:159], v[184:187]
	v_mfma_f32_16x16x32_bf16 v[188:191], v[44:47], v[160:163], v[188:191]
	v_mfma_f32_16x16x32_bf16 v[192:195], v[36:39], v[160:163], v[192:195]
	v_mfma_f32_16x16x32_bf16 v[196:199], v[48:51], v[148:151], v[80:83]
	v_mfma_f32_16x16x32_bf16 v[200:203], v[40:43], v[148:151], v[84:87]
	v_mfma_f32_16x16x32_bf16 v[196:199], v[44:47], v[152:155], v[196:199]
	v_mfma_f32_16x16x32_bf16 v[200:203], v[36:39], v[152:155], v[200:203]
	s_nop 2
	v_exp_f32_e32 v188, v188
	v_exp_f32_e32 v189, v189
	v_exp_f32_e32 v190, v190
	v_exp_f32_e32 v191, v191
	v_exp_f32_e32 v192, v192
	v_exp_f32_e32 v193, v193
	v_exp_f32_e32 v194, v194
	v_exp_f32_e32 v195, v195
	v_cvt_pk_bf16_f32 v246, v188, v189
	v_cvt_pk_bf16_f32 v247, v190, v191
	v_cvt_pk_bf16_f32 v248, v192, v193
	v_cvt_pk_bf16_f32 v249, v194, v195
	v_add_f32_e32 v188, v188, v189
	v_add_f32_e32 v190, v190, v191
	v_add_f32_e32 v192, v192, v193
	v_add_f32_e32 v194, v194, v195
	v_add_f32_e32 v188, v188, v190
	v_add_f32_e32 v192, v192, v194
	v_add_f32_e32 v188, v188, v192
	v_add_f32_e32 v225, v225, v188
	v_exp_f32_e32 v196, v196
	v_exp_f32_e32 v197, v197
	v_exp_f32_e32 v198, v198
	v_exp_f32_e32 v199, v199
	v_mfma_f32_16x16x32_bf16 v[112:115], v[16:19], v[246:249], v[112:115]
	v_exp_f32_e32 v200, v200
	v_exp_f32_e32 v201, v201
	v_exp_f32_e32 v202, v202
	v_exp_f32_e32 v203, v203
	v_mfma_f32_16x16x32_bf16 v[108:111], v[12:15], v[246:249], v[108:111]
	v_cvt_pk_bf16_f32 v92, v196, v197
	v_cvt_pk_bf16_f32 v93, v198, v199
	v_cvt_pk_bf16_f32 v94, v200, v201
	v_cvt_pk_bf16_f32 v95, v202, v203
	v_mfma_f32_16x16x32_bf16 v[104:107], v[8:11], v[246:249], v[104:107]
	v_add_f32_e32 v196, v196, v197
	v_add_f32_e32 v198, v198, v199
	v_add_f32_e32 v200, v200, v201
	v_add_f32_e32 v202, v202, v203
	v_mfma_f32_16x16x32_bf16 v[100:103], v[4:7], v[246:249], v[100:103]
	v_add_f32_e32 v196, v196, v198
	v_add_f32_e32 v200, v200, v202
	v_add_f32_e32 v196, v196, v200
	v_add_f32_e32 v224, v224, v196
	v_mfma_f32_16x16x32_bf16 v[128:131], v[16:19], v[92:95], v[128:131]
	v_mfma_f32_16x16x32_bf16 v[124:127], v[12:15], v[92:95], v[124:127]
	v_mfma_f32_16x16x32_bf16 v[120:123], v[8:11], v[92:95], v[120:123]
	v_mfma_f32_16x16x32_bf16 v[116:119], v[4:7], v[92:95], v[116:119]
	v_add_u32_e32 v240, 0x100, v240
	s_waitcnt lgkmcnt(0)
	s_waitcnt vmcnt(2)
	s_barrier
	s_add_u32 s20, s92, 3
	s_cmp_ge_u32 s20, s80
	s_cbranch_scc1 .Latt_sk23
	s_add_u32 s20, s20, s93
	s_lshl_b32 s21, s20, 16
	s_add_u32 s21, s21, s61
	s_lshl_b32 s22, s20, 7
	s_add_u32 s22, s22, s62
	s_add_u32 m0, s95, s84
	s_add_u32 s86, s95, s84
	s_add_u32 s86, s86, 0x2000
	buffer_load_dwordx4 v235, s[24:27], s21 offen lds
	s_mov_b32 m0, s86
	s_nop 0
	buffer_load_dwordx4 v250, s[40:43], s22 offen lds

.Latt_cs24:
	v_add_u32_e32 v251, s23, v233
	v_add_u32_e32 v253, s33, v234
	ds_read_b128 v[48:51], v251 offset:0
	ds_read_b128 v[40:43], v251 offset:4096
	ds_read_b128 v[44:47], v251 offset:2048
	ds_read_b128 v[36:39], v251 offset:6144
	ds_read_b128 v[16:19], v253 offset:0
	ds_read_b128 v[12:15], v253 offset:2048
	ds_read_b128 v[8:11], v253 offset:4096
	ds_read_b128 v[4:7], v253 offset:6144
	v_mfma_f32_16x16x32_bf16 v[188:191], v[176:179], v[156:159], v[80:83]
	v_mfma_f32_16x16x32_bf16 v[192:195], v[168:171], v[156:159], v[84:87]
	v_mfma_f32_16x16x32_bf16 v[188:191], v[172:175], v[160:163], v[188:191]
	v_mfma_f32_16x16x32_bf16 v[192:195], v[164:167], v[160:163], v[192:195]
	s_nop 6
	v_exp_f32_e32 v188, v188
	v_exp_f32_e32 v189, v189
	v_exp_f32_e32 v190, v190
	v_exp_f32_e32 v191, v191
	v_exp_f32_e32 v192, v192
	v_exp_f32_e32 v193, v193
	v_exp_f32_e32 v194, v194
	v_exp_f32_e32 v195, v195
	v_cvt_pk_bf16_f32 v246, v188, v189
	v_cvt_pk_bf16_f32 v247, v190, v191
	v_cvt_pk_bf16_f32 v248, v192, v193
	v_cvt_pk_bf16_f32 v249, v194, v195
	v_add_f32_e32 v188, v188, v189
	v_add_f32_e32 v190, v190, v191
	v_add_f32_e32 v192, v192, v193
	v_add_f32_e32 v194, v194, v195
	v_add_f32_e32 v188, v188, v190
	v_add_f32_e32 v192, v192, v194
	v_add_f32_e32 v188, v188, v192
	v_add_f32_e32 v225, v225, v188
	v_mfma_f32_16x16x32_bf16 v[112:115], v[32:35], v[246:249], v[112:115]
	v_mfma_f32_16x16x32_bf16 v[108:111], v[28:31], v[246:249], v[108:111]
	v_mfma_f32_16x16x32_bf16 v[104:107], v[24:27], v[246:249], v[104:107]
	v_mfma_f32_16x16x32_bf16 v[100:103], v[20:23], v[246:249], v[100:103]
	v_add_u32_e32 v240, 0x100, v240
	s_sub_u32 s91, 8, s60
	s_branch .Latt_CB

.Latt_F0:
	s_waitcnt lgkmcnt(0)
	s_waitcnt vmcnt(2)
	s_barrier
	s_add_u32 s20, s92, 3
	s_cmp_ge_u32 s20, s80
	s_cbranch_scc1 .Latt_sk25
	s_add_u32 s20, s20, s93
	s_lshl_b32 s21, s20, 16
	s_add_u32 s21, s21, s61
	s_lshl_b32 s22, s20, 7
	s_add_u32 s22, s22, s62
	s_add_u32 m0, s95, s84
	s_add_u32 s86, s95, s84
	s_add_u32 s86, s86, 0x2000
	buffer_load_dwordx4 v235, s[24:27], s21 offen lds
	s_mov_b32 m0, s86
	s_nop 0
	buffer_load_dwordx4 v250, s[40:43], s22 offen lds

.Latt_cs32:
	v_add_u32_e32 v251, s23, v233
	v_add_u32_e32 v253, s33, v234
	ds_read_b128 v[176:179], v251 offset:0
	ds_read_b128 v[168:171], v251 offset:4096
	ds_read_b128 v[172:175], v251 offset:2048
	ds_read_b128 v[164:167], v251 offset:6144
	ds_read_b128 v[32:35], v253 offset:0
	ds_read_b128 v[28:31], v253 offset:2048
	ds_read_b128 v[24:27], v253 offset:4096
	ds_read_b128 v[20:23], v253 offset:6144
	v_mfma_f32_16x16x32_bf16 v[188:191], v[48:51], v[156:159], v[204:207]
	v_mfma_f32_16x16x32_bf16 v[192:195], v[40:43], v[156:159], v[208:211]
	v_mfma_f32_16x16x32_bf16 v[188:191], v[44:47], v[160:163], v[188:191]
	v_mfma_f32_16x16x32_bf16 v[192:195], v[36:39], v[160:163], v[192:195]
	ds_read2_b32 v[204:205], v240 offset0:0 offset1:1
	ds_read2_b32 v[206:207], v240 offset0:2 offset1:3
	ds_read2_b32 v[208:209], v240 offset0:4 offset1:5
	ds_read2_b32 v[210:211], v240 offset0:6 offset1:7
	v_mfma_f32_16x16x32_bf16 v[196:199], v[48:51], v[148:151], v[212:215]
	v_mfma_f32_16x16x32_bf16 v[200:203], v[40:43], v[148:151], v[242:245]
	v_mfma_f32_16x16x32_bf16 v[196:199], v[44:47], v[152:155], v[196:199]
	v_mfma_f32_16x16x32_bf16 v[200:203], v[36:39], v[152:155], v[200:203]
	v_exp_f32_e32 v188, v188
	v_exp_f32_e32 v189, v189
	v_exp_f32_e32 v190, v190
	v_exp_f32_e32 v191, v191
	v_exp_f32_e32 v192, v192
	v_exp_f32_e32 v193, v193
	v_exp_f32_e32 v194, v194
	v_exp_f32_e32 v195, v195
	v_cvt_pk_bf16_f32 v246, v188, v189
	v_cvt_pk_bf16_f32 v247, v190, v191
	v_cvt_pk_bf16_f32 v248, v192, v193
	v_cvt_pk_bf16_f32 v249, v194, v195
	v_add_f32_e32 v188, v188, v189
	v_add_f32_e32 v190, v190, v191
	v_add_f32_e32 v192, v192, v193
	v_add_f32_e32 v194, v194, v195
	v_add_f32_e32 v188, v188, v190
	v_add_f32_e32 v192, v192, v194
	v_add_f32_e32 v188, v188, v192
	v_add_f32_e32 v225, v225, v188
	v_mfma_f32_16x16x32_bf16 v[188:191], v[48:51], v[140:143], v[180:183]
	v_mfma_f32_16x16x32_bf16 v[192:195], v[40:43], v[140:143], v[184:187]
	v_mfma_f32_16x16x32_bf16 v[188:191], v[44:47], v[144:147], v[188:191]
	v_mfma_f32_16x16x32_bf16 v[192:195], v[36:39], v[144:147], v[192:195]
	v_exp_f32_e32 v196, v196
	v_exp_f32_e32 v197, v197
	v_exp_f32_e32 v198, v198
	v_exp_f32_e32 v199, v199
	v_mfma_f32_16x16x32_bf16 v[112:115], v[16:19], v[246:249], v[112:115]
	v_exp_f32_e32 v200, v200
	v_exp_f32_e32 v201, v201
	v_exp_f32_e32 v202, v202
	v_exp_f32_e32 v203, v203
	v_mfma_f32_16x16x32_bf16 v[108:111], v[12:15], v[246:249], v[108:111]
	v_cvt_pk_bf16_f32 v92, v196, v197
	v_cvt_pk_bf16_f32 v93, v198, v199
	v_cvt_pk_bf16_f32 v94, v200, v201
	v_cvt_pk_bf16_f32 v95, v202, v203
	v_mfma_f32_16x16x32_bf16 v[104:107], v[8:11], v[246:249], v[104:107]
	v_add_f32_e32 v196, v196, v197
	v_add_f32_e32 v198, v198, v199
	v_add_f32_e32 v200, v200, v201
	v_add_f32_e32 v202, v202, v203
	v_mfma_f32_16x16x32_bf16 v[100:103], v[4:7], v[246:249], v[100:103]
	v_add_f32_e32 v196, v196, v198
	v_add_f32_e32 v200, v200, v202
	v_add_f32_e32 v196, v196, v200
	v_add_f32_e32 v224, v224, v196
	v_mfma_f32_16x16x32_bf16 v[196:199], v[48:51], v[132:135], v[80:83]
	v_mfma_f32_16x16x32_bf16 v[200:203], v[40:43], v[132:135], v[84:87]
	v_mfma_f32_16x16x32_bf16 v[196:199], v[44:47], v[136:139], v[196:199]
	v_mfma_f32_16x16x32_bf16 v[200:203], v[36:39], v[136:139], v[200:203]
	v_exp_f32_e32 v188, v188
	v_exp_f32_e32 v189, v189
	v_exp_f32_e32 v190, v190
	v_exp_f32_e32 v191, v191
	v_mfma_f32_16x16x32_bf16 v[128:131], v[16:19], v[92:95], v[128:131]
	v_exp_f32_e32 v192, v192
	v_exp_f32_e32 v193, v193
	v_exp_f32_e32 v194, v194
	v_exp_f32_e32 v195, v195
	v_mfma_f32_16x16x32_bf16 v[124:127], v[12:15], v[92:95], v[124:127]
	v_cvt_pk_bf16_f32 v246, v188, v189
	v_cvt_pk_bf16_f32 v247, v190, v191
	v_cvt_pk_bf16_f32 v248, v192, v193
	v_cvt_pk_bf16_f32 v249, v194, v195
	v_mfma_f32_16x16x32_bf16 v[120:123], v[8:11], v[92:95], v[120:123]
	v_add_f32_e32 v188, v188, v189
	v_add_f32_e32 v190, v190, v191
	v_add_f32_e32 v192, v192, v193
	v_add_f32_e32 v194, v194, v195
	v_mfma_f32_16x16x32_bf16 v[116:119], v[4:7], v[92:95], v[116:119]
	v_add_f32_e32 v188, v188, v190
	v_add_f32_e32 v192, v192, v194
	v_add_f32_e32 v188, v188, v192
	v_add_f32_e32 v223, v223, v188
	v_exp_f32_e32 v196, v196
	v_exp_f32_e32 v197, v197
	v_exp_f32_e32 v198, v198
	v_exp_f32_e32 v199, v199
	v_mfma_f32_16x16x32_bf16 v[64:67], v[16:19], v[246:249], v[64:67]
	v_exp_f32_e32 v200, v200
	v_exp_f32_e32 v201, v201
	v_exp_f32_e32 v202, v202
	v_exp_f32_e32 v203, v203
	v_mfma_f32_16x16x32_bf16 v[60:63], v[12:15], v[246:249], v[60:63]
	v_cvt_pk_bf16_f32 v92, v196, v197
	v_cvt_pk_bf16_f32 v93, v198, v199
	v_cvt_pk_bf16_f32 v94, v200, v201
	v_cvt_pk_bf16_f32 v95, v202, v203
	v_mfma_f32_16x16x32_bf16 v[56:59], v[8:11], v[246:249], v[56:59]
	v_add_f32_e32 v196, v196, v197
	v_add_f32_e32 v198, v198, v199
	v_add_f32_e32 v200, v200, v201
	v_add_f32_e32 v202, v202, v203
	v_mfma_f32_16x16x32_bf16 v[52:55], v[4:7], v[246:249], v[52:55]
	v_add_f32_e32 v196, v196, v198
	v_add_f32_e32 v200, v200, v202
	v_add_f32_e32 v196, v196, v200
	v_add_f32_e32 v222, v222, v196
	s_waitcnt lgkmcnt(0)
	v_sub_f32_e32 v204, v204, v239
	v_sub_f32_e32 v205, v205, v239
	v_sub_f32_e32 v206, v206, v239
	v_mfma_f32_16x16x32_bf16 v[96:99], v[16:19], v[92:95], v[96:99]
	v_sub_f32_e32 v207, v207, v239
	v_sub_f32_e32 v208, v208, v239
	v_sub_f32_e32 v209, v209, v239
	v_mfma_f32_16x16x32_bf16 v[88:91], v[12:15], v[92:95], v[88:91]
	v_sub_f32_e32 v210, v210, v239
	v_sub_f32_e32 v211, v211, v239
	v_cndmask_b32_e64 v204, v238, v204, s[0:1]
	v_mfma_f32_16x16x32_bf16 v[72:75], v[8:11], v[92:95], v[72:75]
	v_cndmask_b32_e64 v205, v238, v205, s[6:7]
	v_cndmask_b32_e64 v206, v238, v206, s[8:9]
	v_cndmask_b32_e64 v207, v238, v207, s[10:11]
	v_mfma_f32_16x16x32_bf16 v[68:71], v[4:7], v[92:95], v[68:71]
	v_cndmask_b32_e64 v208, v238, v208, s[12:13]
	v_cndmask_b32_e64 v209, v238, v209, s[14:15]
	v_cndmask_b32_e64 v210, v238, v210, s[16:17]
	v_cndmask_b32_e64 v211, v238, v211, s[18:19]
	v_add_u32_e32 v240, 0x100, v240
	s_sub_u32 s91, s91, 1
	s_cmp_lg_u32 s91, 0
	s_cbranch_scc1 .Latt_F0
	s_sub_u32 s91, 8, s60

.Latt_cs34:
	v_add_u32_e32 v251, s23, v233
	v_add_u32_e32 v253, s33, v234
	ds_read_b128 v[48:51], v251 offset:0
	ds_read_b128 v[40:43], v251 offset:4096
	ds_read_b128 v[44:47], v251 offset:2048
	ds_read_b128 v[36:39], v251 offset:6144
	ds_read_b128 v[16:19], v253 offset:0
	ds_read_b128 v[12:15], v253 offset:2048
	ds_read_b128 v[8:11], v253 offset:4096
	ds_read_b128 v[4:7], v253 offset:6144
	v_mfma_f32_16x16x32_bf16 v[188:191], v[176:179], v[132:135], v[76:79]
	v_mfma_f32_16x16x32_bf16 v[192:195], v[168:171], v[132:135], v[76:79]
	v_mfma_f32_16x16x32_bf16 v[188:191], v[172:175], v[136:139], v[188:191]
	v_mfma_f32_16x16x32_bf16 v[192:195], v[164:167], v[136:139], v[192:195]
	v_mfma_f32_16x16x32_bf16 v[196:199], v[176:179], v[140:143], v[76:79]
	v_mfma_f32_16x16x32_bf16 v[200:203], v[168:171], v[140:143], v[76:79]
	v_mfma_f32_16x16x32_bf16 v[196:199], v[172:175], v[144:147], v[196:199]
	v_mfma_f32_16x16x32_bf16 v[200:203], v[164:167], v[144:147], v[200:203]
	s_nop 2
	v_exp_f32_e32 v188, v188
	v_exp_f32_e32 v189, v189
	v_exp_f32_e32 v190, v190
	v_exp_f32_e32 v191, v191
	v_exp_f32_e32 v192, v192
	v_exp_f32_e32 v193, v193
	v_exp_f32_e32 v194, v194
	v_exp_f32_e32 v195, v195
	v_cvt_pk_bf16_f32 v246, v188, v189
	v_cvt_pk_bf16_f32 v247, v190, v191
	v_cvt_pk_bf16_f32 v248, v192, v193
	v_cvt_pk_bf16_f32 v249, v194, v195
	v_add_f32_e32 v188, v188, v189
	v_add_f32_e32 v190, v190, v191
	v_add_f32_e32 v192, v192, v193
	v_add_f32_e32 v194, v194, v195
	v_add_f32_e32 v188, v188, v190
	v_add_f32_e32 v192, v192, v194
	v_add_f32_e32 v188, v188, v192
	v_add_f32_e32 v222, v222, v188
	v_mfma_f32_16x16x32_bf16 v[188:191], v[176:179], v[148:151], v[76:79]
	v_mfma_f32_16x16x32_bf16 v[192:195], v[168:171], v[148:151], v[76:79]
	v_mfma_f32_16x16x32_bf16 v[188:191], v[172:175], v[152:155], v[188:191]
	v_mfma_f32_16x16x32_bf16 v[192:195], v[164:167], v[152:155], v[192:195]
	v_exp_f32_e32 v196, v196
	v_exp_f32_e32 v197, v197
	v_exp_f32_e32 v198, v198
	v_exp_f32_e32 v199, v199
	v_mfma_f32_16x16x32_bf16 v[96:99], v[32:35], v[246:249], v[96:99]
	v_exp_f32_e32 v200, v200
	v_exp_f32_e32 v201, v201
	v_exp_f32_e32 v202, v202
	v_exp_f32_e32 v203, v203
	v_mfma_f32_16x16x32_bf16 v[88:91], v[28:31], v[246:249], v[88:91]
	v_cvt_pk_bf16_f32 v92, v196, v197
	v_cvt_pk_bf16_f32 v93, v198, v199
	v_cvt_pk_bf16_f32 v94, v200, v201
	v_cvt_pk_bf16_f32 v95, v202, v203
	v_mfma_f32_16x16x32_bf16 v[72:75], v[24:27], v[246:249], v[72:75]
	v_add_f32_e32 v196, v196, v197
	v_add_f32_e32 v198, v198, v199
	v_add_f32_e32 v200, v200, v201
	v_add_f32_e32 v202, v202, v203
	v_mfma_f32_16x16x32_bf16 v[68:71], v[20:23], v[246:249], v[68:71]
	v_add_f32_e32 v196, v196, v198
	v_add_f32_e32 v200, v200, v202
	v_add_f32_e32 v196, v196, v200
	v_add_f32_e32 v223, v223, v196
	v_mfma_f32_16x16x32_bf16 v[196:199], v[176:179], v[156:159], v[76:79]
	v_mfma_f32_16x16x32_bf16 v[200:203], v[168:171], v[156:159], v[76:79]
	v_mfma_f32_16x16x32_bf16 v[196:199], v[172:175], v[160:163], v[196:199]
	v_mfma_f32_16x16x32_bf16 v[200:203], v[164:167], v[160:163], v[200:203]
	v_exp_f32_e32 v188, v188
	v_exp_f32_e32 v189, v189
	v_exp_f32_e32 v190, v190
	v_exp_f32_e32 v191, v191
	v_mfma_f32_16x16x32_bf16 v[64:67], v[32:35], v[92:95], v[64:67]
	v_exp_f32_e32 v192, v192
	v_exp_f32_e32 v193, v193
	v_exp_f32_e32 v194, v194
	v_exp_f32_e32 v195, v195
	v_mfma_f32_16x16x32_bf16 v[60:63], v[28:31], v[92:95], v[60:63]
	v_cvt_pk_bf16_f32 v246, v188, v189
	v_cvt_pk_bf16_f32 v247, v190, v191
	v_cvt_pk_bf16_f32 v248, v192, v193
	v_cvt_pk_bf16_f32 v249, v194, v195
	v_mfma_f32_16x16x32_bf16 v[56:59], v[24:27], v[92:95], v[56:59]
	v_add_f32_e32 v188, v188, v189
	v_add_f32_e32 v190, v190, v191
	v_add_f32_e32 v192, v192, v193
	v_add_f32_e32 v194, v194, v195
	v_mfma_f32_16x16x32_bf16 v[52:55], v[20:23], v[92:95], v[52:55]
	v_add_f32_e32 v188, v188, v190
	v_add_f32_e32 v192, v192, v194
	v_add_f32_e32 v188, v188, v192
	v_add_f32_e32 v224, v224, v188
	v_exp_f32_e32 v196, v196
	v_exp_f32_e32 v197, v197
	v_exp_f32_e32 v198, v198
	v_exp_f32_e32 v199, v199
	v_mfma_f32_16x16x32_bf16 v[128:131], v[32:35], v[246:249], v[128:131]
	v_exp_f32_e32 v200, v200
	v_exp_f32_e32 v201, v201
	v_exp_f32_e32 v202, v202
	v_exp_f32_e32 v203, v203
	v_mfma_f32_16x16x32_bf16 v[124:127], v[28:31], v[246:249], v[124:127]
	v_cvt_pk_bf16_f32 v92, v196, v197
	v_cvt_pk_bf16_f32 v93, v198, v199
	v_cvt_pk_bf16_f32 v94, v200, v201
	v_cvt_pk_bf16_f32 v95, v202, v203
	v_mfma_f32_16x16x32_bf16 v[120:123], v[24:27], v[246:249], v[120:123]
	v_add_f32_e32 v196, v196, v197
	v_add_f32_e32 v198, v198, v199
	v_add_f32_e32 v200, v200, v201
	v_add_f32_e32 v202, v202, v203
	v_mfma_f32_16x16x32_bf16 v[116:119], v[20:23], v[246:249], v[116:119]
	v_add_f32_e32 v196, v196, v198
	v_add_f32_e32 v200, v200, v202
	v_add_f32_e32 v196, v196, v200
	v_add_f32_e32 v225, v225, v196
	v_mfma_f32_16x16x32_bf16 v[112:115], v[32:35], v[92:95], v[112:115]
	v_mfma_f32_16x16x32_bf16 v[108:111], v[28:31], v[92:95], v[108:111]
	v_mfma_f32_16x16x32_bf16 v[104:107], v[24:27], v[92:95], v[104:107]
	v_mfma_f32_16x16x32_bf16 v[100:103], v[20:23], v[92:95], v[100:103]
	s_sub_u32 s91, s91, 1
	s_cmp_eq_u32 s91, 0
	s_cbranch_scc1 .Latt_cdone

.Latt_cs36:
	v_add_u32_e32 v251, s23, v233
	v_add_u32_e32 v253, s33, v234
	ds_read_b128 v[176:179], v251 offset:0
	ds_read_b128 v[168:171], v251 offset:4096
	ds_read_b128 v[172:175], v251 offset:2048
	ds_read_b128 v[164:167], v251 offset:6144
	ds_read_b128 v[32:35], v253 offset:0
	ds_read_b128 v[28:31], v253 offset:2048
	ds_read_b128 v[24:27], v253 offset:4096
	ds_read_b128 v[20:23], v253 offset:6144
	v_mfma_f32_16x16x32_bf16 v[188:191], v[48:51], v[132:135], v[76:79]
	v_mfma_f32_16x16x32_bf16 v[192:195], v[40:43], v[132:135], v[76:79]
	v_mfma_f32_16x16x32_bf16 v[188:191], v[44:47], v[136:139], v[188:191]
	v_mfma_f32_16x16x32_bf16 v[192:195], v[36:39], v[136:139], v[192:195]
	v_mfma_f32_16x16x32_bf16 v[196:199], v[48:51], v[140:143], v[76:79]
	v_mfma_f32_16x16x32_bf16 v[200:203], v[40:43], v[140:143], v[76:79]
	v_mfma_f32_16x16x32_bf16 v[196:199], v[44:47], v[144:147], v[196:199]
	v_mfma_f32_16x16x32_bf16 v[200:203], v[36:39], v[144:147], v[200:203]
	s_nop 2
	v_exp_f32_e32 v188, v188
	v_exp_f32_e32 v189, v189
	v_exp_f32_e32 v190, v190
	v_exp_f32_e32 v191, v191
	v_exp_f32_e32 v192, v192
	v_exp_f32_e32 v193, v193
	v_exp_f32_e32 v194, v194
	v_exp_f32_e32 v195, v195
	v_cvt_pk_bf16_f32 v246, v188, v189
	v_cvt_pk_bf16_f32 v247, v190, v191
	v_cvt_pk_bf16_f32 v248, v192, v193
	v_cvt_pk_bf16_f32 v249, v194, v195
	v_add_f32_e32 v188, v188, v189
	v_add_f32_e32 v190, v190, v191
	v_add_f32_e32 v192, v192, v193
	v_add_f32_e32 v194, v194, v195
	v_add_f32_e32 v188, v188, v190
	v_add_f32_e32 v192, v192, v194
	v_add_f32_e32 v188, v188, v192
	v_add_f32_e32 v222, v222, v188
	v_mfma_f32_16x16x32_bf16 v[188:191], v[48:51], v[148:151], v[76:79]
	v_mfma_f32_16x16x32_bf16 v[192:195], v[40:43], v[148:151], v[76:79]
	v_mfma_f32_16x16x32_bf16 v[188:191], v[44:47], v[152:155], v[188:191]
	v_mfma_f32_16x16x32_bf16 v[192:195], v[36:39], v[152:155], v[192:195]
	v_exp_f32_e32 v196, v196
	v_exp_f32_e32 v197, v197
	v_exp_f32_e32 v198, v198
	v_exp_f32_e32 v199, v199
	v_mfma_f32_16x16x32_bf16 v[96:99], v[16:19], v[246:249], v[96:99]
	v_exp_f32_e32 v200, v200
	v_exp_f32_e32 v201, v201
	v_exp_f32_e32 v202, v202
	v_exp_f32_e32 v203, v203
	v_mfma_f32_16x16x32_bf16 v[88:91], v[12:15], v[246:249], v[88:91]
	v_cvt_pk_bf16_f32 v92, v196, v197
	v_cvt_pk_bf16_f32 v93, v198, v199
	v_cvt_pk_bf16_f32 v94, v200, v201
	v_cvt_pk_bf16_f32 v95, v202, v203
	v_mfma_f32_16x16x32_bf16 v[72:75], v[8:11], v[246:249], v[72:75]
	v_add_f32_e32 v196, v196, v197
	v_add_f32_e32 v198, v198, v199
	v_add_f32_e32 v200, v200, v201
	v_add_f32_e32 v202, v202, v203
	v_mfma_f32_16x16x32_bf16 v[68:71], v[4:7], v[246:249], v[68:71]
	v_add_f32_e32 v196, v196, v198
	v_add_f32_e32 v200, v200, v202
	v_add_f32_e32 v196, v196, v200
	v_add_f32_e32 v223, v223, v196
	v_mfma_f32_16x16x32_bf16 v[196:199], v[48:51], v[156:159], v[76:79]
	v_mfma_f32_16x16x32_bf16 v[200:203], v[40:43], v[156:159], v[76:79]
	v_mfma_f32_16x16x32_bf16 v[196:199], v[44:47], v[160:163], v[196:199]
	v_mfma_f32_16x16x32_bf16 v[200:203], v[36:39], v[160:163], v[200:203]
	v_exp_f32_e32 v188, v188
	v_exp_f32_e32 v189, v189
	v_exp_f32_e32 v190, v190
	v_exp_f32_e32 v191, v191
	v_mfma_f32_16x16x32_bf16 v[64:67], v[16:19], v[92:95], v[64:67]
	v_exp_f32_e32 v192, v192
	v_exp_f32_e32 v193, v193
	v_exp_f32_e32 v194, v194
	v_exp_f32_e32 v195, v195
	v_mfma_f32_16x16x32_bf16 v[60:63], v[12:15], v[92:95], v[60:63]
	v_cvt_pk_bf16_f32 v246, v188, v189
	v_cvt_pk_bf16_f32 v247, v190, v191
	v_cvt_pk_bf16_f32 v248, v192, v193
	v_cvt_pk_bf16_f32 v249, v194, v195
	v_mfma_f32_16x16x32_bf16 v[56:59], v[8:11], v[92:95], v[56:59]
	v_add_f32_e32 v188, v188, v189
	v_add_f32_e32 v190, v190, v191
	v_add_f32_e32 v192, v192, v193
	v_add_f32_e32 v194, v194, v195
	v_mfma_f32_16x16x32_bf16 v[52:55], v[4:7], v[92:95], v[52:55]
	v_add_f32_e32 v188, v188, v190
	v_add_f32_e32 v192, v192, v194
	v_add_f32_e32 v188, v188, v192
	v_add_f32_e32 v224, v224, v188
	v_exp_f32_e32 v196, v196
	v_exp_f32_e32 v197, v197
	v_exp_f32_e32 v198, v198
	v_exp_f32_e32 v199, v199
	v_mfma_f32_16x16x32_bf16 v[128:131], v[16:19], v[246:249], v[128:131]
	v_exp_f32_e32 v200, v200
	v_exp_f32_e32 v201, v201
	v_exp_f32_e32 v202, v202
	v_exp_f32_e32 v203, v203
	v_mfma_f32_16x16x32_bf16 v[124:127], v[12:15], v[246:249], v[124:127]
	v_cvt_pk_bf16_f32 v92, v196, v197
	v_cvt_pk_bf16_f32 v93, v198, v199
	v_cvt_pk_bf16_f32 v94, v200, v201
	v_cvt_pk_bf16_f32 v95, v202, v203
	v_mfma_f32_16x16x32_bf16 v[120:123], v[8:11], v[246:249], v[120:123]
	v_add_f32_e32 v196, v196, v197
	v_add_f32_e32 v198, v198, v199
	v_add_f32_e32 v200, v200, v201
	v_add_f32_e32 v202, v202, v203
	v_mfma_f32_16x16x32_bf16 v[116:119], v[4:7], v[246:249], v[116:119]
	v_add_f32_e32 v196, v196, v198
	v_add_f32_e32 v200, v200, v202
	v_add_f32_e32 v196, v196, v200
	v_add_f32_e32 v225, v225, v196
	v_mfma_f32_16x16x32_bf16 v[112:115], v[16:19], v[92:95], v[112:115]
	v_mfma_f32_16x16x32_bf16 v[108:111], v[12:15], v[92:95], v[108:111]
	v_mfma_f32_16x16x32_bf16 v[104:107], v[8:11], v[92:95], v[104:107]
	v_mfma_f32_16x16x32_bf16 v[100:103], v[4:7], v[92:95], v[100:103]
	s_sub_u32 s91, s91, 1
	s_cmp_lg_u32 s91, 0
	s_cbranch_scc1 .Latt_CA
.Latt_cdone:
	s_nop 7
	s_cmp_eq_u32 s94, 1
	s_cbranch_scc1 .Latt_went
	s_cmp_eq_u32 s76, 8
	s_cbranch_scc0 .Latt_end
	s_waitcnt lgkmcnt(0)
	s_waitcnt vmcnt(2)
	s_barrier
	s_add_u32 s20, s92, 3
	s_cmp_ge_u32 s20, s80
	s_cbranch_scc1 .Latt_sk37
	s_add_u32 s20, s20, s93
	s_lshl_b32 s21, s20, 16
	s_add_u32 s21, s21, s61
	s_lshl_b32 s22, s20, 7
	s_add_u32 s22, s22, s62
	s_add_u32 m0, s95, s84
	s_add_u32 s86, s95, s84
	s_add_u32 s86, s86, 0x2000
	buffer_load_dwordx4 v235, s[24:27], s21 offen lds
	s_mov_b32 m0, s86
	s_nop 0
	buffer_load_dwordx4 v250, s[40:43], s22 offen lds

.Latt_cs42:
.Latt_end:
	s_waitcnt vmcnt(0) lgkmcnt(0)
	s_barrier
	s_branch .LBB0_450

	.amdhsa_kernel _Z6k_mega6Params
		.amdhsa_group_segment_fixed_size 16384
		.amdhsa_private_segment_fixed_size 0
		.amdhsa_kernarg_size 504
		.amdhsa_user_sgpr_count 2
		.amdhsa_user_sgpr_dispatch_ptr 0
		.amdhsa_user_sgpr_queue_ptr 0
		.amdhsa_user_sgpr_kernarg_segment_ptr 1
		.amdhsa_user_sgpr_dispatch_id 0
		.amdhsa_user_sgpr_kernarg_preload_length 0
		.amdhsa_user_sgpr_kernarg_preload_offset 0
		.amdhsa_user_sgpr_private_segment_size 0
		.amdhsa_uses_dynamic_stack 0
		.amdhsa_enable_private_segment 0
		.amdhsa_system_sgpr_workgroup_id_x 1
		.amdhsa_system_sgpr_workgroup_id_y 0
		.amdhsa_system_sgpr_workgroup_id_z 0
		.amdhsa_system_sgpr_workgroup_info 0
		.amdhsa_system_vgpr_workitem_id 2
		.amdhsa_next_free_vgpr 256
		.amdhsa_next_free_sgpr 98
		.amdhsa_accum_offset 256
		.amdhsa_reserve_vcc 1
		.amdhsa_float_round_mode_32 0
		.amdhsa_float_round_mode_16_64 0
		.amdhsa_float_denorm_mode_32 3
		.amdhsa_float_denorm_mode_16_64 3
		.amdhsa_dx10_clamp 1
		.amdhsa_ieee_mode 1
		.amdhsa_fp16_overflow 0
		.amdhsa_tg_split 0
		.amdhsa_exception_fp_ieee_invalid_op 0
		.amdhsa_exception_fp_denorm_src 0
		.amdhsa_exception_fp_ieee_div_zero 0
		.amdhsa_exception_fp_ieee_overflow 0
		.amdhsa_exception_fp_ieee_underflow 0
		.amdhsa_exception_fp_ieee_inexact 0
		.amdhsa_exception_int_div_zero 0
	.end_amdhsa_kernel

amdhsa.kernels:
  - .agpr_count:     0
    .args:
      - .offset:         0
        .size:           248
        .value_kind:     by_value
      - .offset:         248
        .size:           4
        .value_kind:     hidden_block_count_x
      - .offset:         252
        .size:           4
        .value_kind:     hidden_block_count_y
      - .offset:         256
        .size:           4
        .value_kind:     hidden_block_count_z
      - .offset:         260
        .size:           2
        .value_kind:     hidden_group_size_x
      - .offset:         262
        .size:           2
        .value_kind:     hidden_group_size_y
      - .offset:         264
        .size:           2
        .value_kind:     hidden_group_size_z
      - .offset:         266
        .size:           2
        .value_kind:     hidden_remainder_x
      - .offset:         268
        .size:           2
        .value_kind:     hidden_remainder_y
      - .offset:         270
        .size:           2
        .value_kind:     hidden_remainder_z
      - .offset:         288
        .size:           8
        .value_kind:     hidden_global_offset_x
      - .offset:         296
        .size:           8
        .value_kind:     hidden_global_offset_y
      - .offset:         304
        .size:           8
        .value_kind:     hidden_global_offset_z
      - .offset:         312
        .size:           2
        .value_kind:     hidden_grid_dims
      - .offset:         336
        .size:           8
        .value_kind:     hidden_multigrid_sync_arg
      - .offset:         368
        .size:           4
        .value_kind:     hidden_dynamic_lds_size
    .group_segment_fixed_size: 16384
    .kernarg_segment_align: 8
    .kernarg_segment_size: 504
    .language:       OpenCL C
    .language_version:
      - 2
      - 0
    .max_flat_workgroup_size: 512
    .name:           _Z6k_mega6Params
    .private_segment_fixed_size: 0
    .sgpr_count:     104
    .sgpr_spill_count: 12
    .symbol:         _Z6k_mega6Params.kd
    .uniform_work_group_size: 1
    .uses_dynamic_stack: false
    .vgpr_count:     256
    .vgpr_spill_count: 0
    .wavefront_size: 64
